# hand-scheduled scan compute loop (batched y-reduce, DPP bank-mask) + staging next-chunk loads issued early
# speedup vs baseline: 1.0127x; 1.0127x over previous
; #define LAS __attribute__((address_space(3)))
; __global__ void __launch_bounds__(512, 2) fwd_megakernel(Params P) {
;     ...
;                         const int row = half * 32 + wid * 8 + rg;
;                         f32x2 Sa = {0.f, 0.f}, Sb = {0.f, 0.f}, Sc = {0.f, 0.f}, Sd = {0.f, 0.f};
;                         f16* yout = Y16 + m0 * 1024 + h * 64 + row;
;                         __builtin_amdgcn_s_setprio(3);
;                         __syncthreads();
; #pragma unroll 1
;                         for (int c = 0; c < T / 32; ++c) {
;                             const LAS unsigned char* buf = lds + (c & 1) * 41984;
;                             const LAS unsigned char* pk = buf + kq * 32; const LAS unsigned char* pv = buf + 1024 + row * 4;
;     ...
;                             f32x4 rg2[2][8]; float rv2[2];
;                             SCAN_LOAD(rg2[0], rv2[0], 0);
; #pragma unroll
;                             for (int tt = 0; tt < 32; tt += 8) {
;                                 float yk = 0.f;
;                                 const f32x4 ge0 = *(const LAS f32x4*)(pk + 40960 + (tt >> 3) * 256), ge1 = *(const LAS f32x4*)(pk + 40960 + (tt >> 3) * 256 + 16);
; #pragma unroll
;                                 for (int j = 0; j < 8; ++j) {
;                                     if (j < 7 || tt + 8 < 32) SCAN_LOAD(rg2[(j + 1) & 1], rv2[(j + 1) & 1], tt + j + 1);
;                                     __builtin_amdgcn_sched_barrier(0);
;                                     const f32x4 (&cur)[8] = rg2[j & 1]; const float curv = rv2[j & 1];
;                                     const f32x2 v2 = {curv, curv};
;                                     const f32x2 pa = v2 * cur[4].xy + Sa, pb = v2 * cur[4].zw + Sb, pc = v2 * cur[5].xy + Sc, pd = v2 * cur[5].zw + Sd;
;                                     f32x2 t0 = Sa * cur[0].xy; t0 = Sb * cur[0].zw + t0;
;                                     f32x2 t1 = Sc * cur[1].xy; t1 = Sd * cur[1].zw + t1;
;                                     const f32x2 t = t0 + t1;
;                                     float sa = sum8(t.x + t.y);
;                                     const f32x2 sa2 = {sa, sa};
;                                     Sa = sa2 * cur[2].xy + pa; Sb = sa2 * cur[2].zw + pb; Sc = sa2 * cur[3].xy + pc; Sd = sa2 * cur[3].zw + pd;
;                                     f32x2 u0 = Sa * cur[6].xy; u0 = Sb * cur[6].zw + u0;
.LBB0_249:
	s_ashr_i32 s92, s3, 5
	s_bfe_u32 s40, s3, 0x40001
	s_and_b32 s39, s3, 1
	s_ashr_i32 s93, s92, 31
	s_mov_b64 s[62:63], -1
	s_and_b64 vcc, exec, s[36:37]
	s_cbranch_vccz .LBB0_253
	v_cndmask_b32_e64 v1, 0, 1, s[90:91]
	v_lshl_add_u32 v2, v1, 5, v180
	s_lshl_b32 s46, s40, 7
	v_ashrrev_i32_e32 v3, 31, v2
	s_lshl_b32 s47, s39, 5
	s_lshl_b64 s[44:45], s[92:93], 23
	s_setprio 3
	s_or_b32 s44, s44, s46
	s_waitcnt vmcnt(21)
	v_mov_b32_e32 v8, s44
	v_mov_b32_e32 v9, s45
	v_lshl_add_u64 v[2:3], v[2:3], 1, v[8:9]
	s_waitcnt vmcnt(19)
	v_mov_b32_e32 v18, 0
	v_add_lshl_u32 v1, s47, v180, 2
	v_lshl_add_u64 v[2:3], v[134:135], 0, v[2:3]
	s_mov_b32 s46, 0
	s_mov_b64 s[94:95], 0
	v_mov_b32_e32 v19, v18
	s_waitcnt vmcnt(18)
	v_mov_b32_e32 v20, v18
	v_mov_b32_e32 v21, v18
	v_mov_b32_e32 v22, v18
	v_mov_b32_e32 v23, v18
	s_waitcnt vmcnt(17)
	v_mov_b32_e32 v24, v18
	v_mov_b32_e32 v25, v18
	s_waitcnt vmcnt(0)
	s_or_b64 s[44:45], s[14:15], s[18:19]
	s_or_b64 s[44:45], s[44:45], s[22:23]
	s_or_b64 s[44:45], s[44:45], s[26:27]
	s_or_b64 s[100:101], s[16:17], s[18:19]
	s_or_b64 s[100:101], s[100:101], s[24:25]
	s_or_b64 s[100:101], s[100:101], s[26:27]
	s_mov_b32 s46, 0x24000000
	v_mov_b32_e32 v26, v181
	v_mov_b32_e32 v27, v1
	v_add_co_u32_e32 v98, vcc, s46, v2
	s_nop 1
	v_addc_co_u32_e32 v99, vcc, 0, v3, vcc
	s_barrier
.Lscan_chunk:
	ds_read_b128 v[28:31], v26 offset:0
	ds_read_b128 v[32:35], v26 offset:16
	ds_read_b128 v[44:47], v26 offset:512
	ds_read_b128 v[48:51], v26 offset:528
	ds_read_b32 v60, v27 offset:1024
	ds_read_b128 v[36:39], v26 offset:256
	ds_read_b128 v[40:43], v26 offset:272
	ds_read_b128 v[52:55], v26 offset:768
	ds_read_b128 v[56:59], v26 offset:784
	ds_read_b128 v[64:67], v26 offset:1280
	ds_read_b128 v[68:71], v26 offset:1296
	ds_read_b128 v[80:83], v26 offset:1792
	ds_read_b128 v[84:87], v26 offset:1808
	ds_read_b32 v96, v27 offset:2304
	ds_read_b128 v[72:75], v26 offset:1536
	ds_read_b128 v[76:79], v26 offset:1552
	ds_read_b128 v[88:91], v26 offset:2048
	ds_read_b128 v[92:95], v26 offset:2064
	s_waitcnt lgkmcnt(15)
	v_pk_mul_f32 v[8:9], v[18:19], v[28:29]
	ds_read_b128 v[124:127], v26 offset:40960
	v_pk_fma_f32 v[8:9], v[20:21], v[30:31], v[8:9]
	ds_read_b128 v[128:131], v26 offset:40976
	s_waitcnt lgkmcnt(15)
	v_pk_fma_f32 v[8:9], v[22:23], v[32:33], v[8:9]
	s_waitcnt lgkmcnt(15)
	v_pk_fma_f32 v[116:117], v[60:61], v[44:45], v[18:19] op_sel_hi:[0,1,1]
	v_pk_fma_f32 v[8:9], v[24:25], v[34:35], v[8:9]
	v_pk_fma_f32 v[118:119], v[60:61], v[46:47], v[20:21] op_sel_hi:[0,1,1]
	v_add_f32_e32 v8, v8, v9
	v_pk_fma_f32 v[120:121], v[60:61], v[48:49], v[22:23] op_sel_hi:[0,1,1]
	v_pk_fma_f32 v[122:123], v[60:61], v[50:51], v[24:25] op_sel_hi:[0,1,1]
	v_add_f32_dpp v8, v8, v8 quad_perm:[1,0,3,2] row_mask:0xf bank_mask:0xf bound_ctrl:1
	ds_read_b128 v[28:31], v26 offset:2560
	ds_read_b128 v[32:35], v26 offset:2576
	v_add_f32_dpp v8, v8, v8 quad_perm:[2,3,0,1] row_mask:0xf bank_mask:0xf bound_ctrl:1
	ds_read_b128 v[44:47], v26 offset:3072
	ds_read_b128 v[48:51], v26 offset:3088
	v_add_f32_dpp v8, v8, v8 row_half_mirror row_mask:0xf bank_mask:0xf bound_ctrl:1
	ds_read_b32 v60, v27 offset:3584
	s_waitcnt lgkmcnt(12)
	v_pk_fma_f32 v[18:19], v[36:37], v[8:9], v[116:117] op_sel_hi:[1,0,1]
	v_pk_fma_f32 v[20:21], v[38:39], v[8:9], v[118:119] op_sel_hi:[1,0,1]
	v_pk_mul_f32 v[10:11], v[18:19], v[64:65]
	v_pk_fma_f32 v[22:23], v[40:41], v[8:9], v[120:121] op_sel_hi:[1,0,1]
	v_pk_fma_f32 v[10:11], v[20:21], v[66:67], v[10:11]
	v_pk_fma_f32 v[24:25], v[42:43], v[8:9], v[122:123] op_sel_hi:[1,0,1]
	v_pk_fma_f32 v[10:11], v[22:23], v[68:69], v[10:11]
	s_waitcnt lgkmcnt(6)
	v_pk_fma_f32 v[116:117], v[96:97], v[80:81], v[18:19] op_sel_hi:[0,1,1]
	v_pk_fma_f32 v[10:11], v[24:25], v[70:71], v[10:11]
	v_pk_fma_f32 v[118:119], v[96:97], v[82:83], v[20:21] op_sel_hi:[0,1,1]
	v_add_f32_e32 v10, v10, v11
	v_pk_fma_f32 v[120:121], v[96:97], v[84:85], v[22:23] op_sel_hi:[0,1,1]
	v_pk_fma_f32 v[122:123], v[96:97], v[86:87], v[24:25] op_sel_hi:[0,1,1]
	v_add_f32_dpp v10, v10, v10 quad_perm:[1,0,3,2] row_mask:0xf bank_mask:0xf bound_ctrl:1
	v_pk_mul_f32 v[12:13], v[52:53], v[18:19]
	ds_read_b128 v[36:39], v26 offset:2816
	v_add_f32_dpp v10, v10, v10 quad_perm:[2,3,0,1] row_mask:0xf bank_mask:0xf bound_ctrl:1
	v_pk_fma_f32 v[12:13], v[54:55], v[20:21], v[12:13]
	ds_read_b128 v[40:43], v26 offset:2832
	v_add_f32_dpp v10, v10, v10 row_half_mirror row_mask:0xf bank_mask:0xf bound_ctrl:1
	v_pk_fma_f32 v[12:13], v[56:57], v[22:23], v[12:13]
	ds_read_b128 v[64:67], v26 offset:3840
	v_pk_fma_f32 v[12:13], v[58:59], v[24:25], v[12:13]
	ds_read_b128 v[52:55], v26 offset:3328
	v_add_f32_e32 v100, v12, v13
	ds_read_b128 v[56:59], v26 offset:3344
	ds_read_b128 v[68:71], v26 offset:3856
	v_pk_fma_f32 v[18:19], v[72:73], v[10:11], v[116:117] op_sel_hi:[1,0,1]
	v_pk_fma_f32 v[20:21], v[74:75], v[10:11], v[118:119] op_sel_hi:[1,0,1]
	s_waitcnt lgkmcnt(6)
; #define LAS __attribute__((address_space(3)))
; __device__ __forceinline__ float sum8(float x) { x += dppf<0xB1>(x); x += dppf<0x4E>(x); x += dppf<0x141>(x); return x; }
; __global__ void __launch_bounds__(512, 2) fwd_megakernel(Params P) {
;     ...
;                             for (int tt = 0; tt < 32; tt += 8) {
;                                 float yk = 0.f;
;                                 const f32x4 ge0 = *(const LAS f32x4*)(pk + 40960 + (tt >> 3) * 256), ge1 = *(const LAS f32x4*)(pk + 40960 + (tt >> 3) * 256 + 16);
; #pragma unroll
;                                 for (int j = 0; j < 8; ++j) {
;                                     if (j < 7 || tt + 8 < 32) SCAN_LOAD(rg2[(j + 1) & 1], rv2[(j + 1) & 1], tt + j + 1);
;                                     __builtin_amdgcn_sched_barrier(0);
;                                     const f32x4 (&cur)[8] = rg2[j & 1]; const float curv = rv2[j & 1];
;                                     const f32x2 v2 = {curv, curv};
;                                     const f32x2 pa = v2 * cur[4].xy + Sa, pb = v2 * cur[4].zw + Sb, pc = v2 * cur[5].xy + Sc, pd = v2 * cur[5].zw + Sd;
;                                     f32x2 t0 = Sa * cur[0].xy; t0 = Sb * cur[0].zw + t0;
;                                     f32x2 t1 = Sc * cur[1].xy; t1 = Sd * cur[1].zw + t1;
;                                     const f32x2 t = t0 + t1;
;                                     float sa = sum8(t.x + t.y);
;                                     const f32x2 sa2 = {sa, sa};
;                                     Sa = sa2 * cur[2].xy + pa; Sb = sa2 * cur[2].zw + pb; Sc = sa2 * cur[3].xy + pc; Sd = sa2 * cur[3].zw + pd;
;                                     f32x2 u0 = Sa * cur[6].xy; u0 = Sb * cur[6].zw + u0;
;                                     f32x2 u1 = Sc * cur[7].xy; u1 = Sd * cur[7].zw + u1;
;                                     const f32x2 u = u0 + u1;
;                                     const float y = sum8(u.x + u.y);
;                                     yk = (kq == j) ? y : yk;
;                                 }
;                                 Sa *= ge0.xy; Sb *= ge0.zw; Sc *= ge1.xy; Sd *= ge1.zw;
;                                 yout[(size_t)(c * 32 + tt + kq) * 1024] = (f16)yk;
	v_pk_mul_f32 v[8:9], v[18:19], v[28:29]
	v_pk_fma_f32 v[22:23], v[76:77], v[10:11], v[120:121] op_sel_hi:[1,0,1]
	v_pk_fma_f32 v[8:9], v[20:21], v[30:31], v[8:9]
	v_pk_fma_f32 v[24:25], v[78:79], v[10:11], v[122:123] op_sel_hi:[1,0,1]
	v_pk_fma_f32 v[8:9], v[22:23], v[32:33], v[8:9]
	ds_read_b128 v[80:83], v26 offset:4352
	v_pk_fma_f32 v[8:9], v[24:25], v[34:35], v[8:9]
	ds_read_b128 v[84:87], v26 offset:4368
	v_add_f32_e32 v8, v8, v9
	ds_read_b32 v96, v27 offset:4864
	v_pk_fma_f32 v[116:117], v[60:61], v[44:45], v[18:19] op_sel_hi:[0,1,1]
	v_add_f32_dpp v8, v8, v8 quad_perm:[1,0,3,2] row_mask:0xf bank_mask:0xf bound_ctrl:1
	v_pk_fma_f32 v[118:119], v[60:61], v[46:47], v[20:21] op_sel_hi:[0,1,1]
	v_pk_fma_f32 v[120:121], v[60:61], v[48:49], v[22:23] op_sel_hi:[0,1,1]
	v_add_f32_dpp v8, v8, v8 quad_perm:[2,3,0,1] row_mask:0xf bank_mask:0xf bound_ctrl:1
	v_pk_fma_f32 v[122:123], v[60:61], v[50:51], v[24:25] op_sel_hi:[0,1,1]
	v_pk_mul_f32 v[14:15], v[88:89], v[18:19]
	v_add_f32_dpp v8, v8, v8 row_half_mirror row_mask:0xf bank_mask:0xf bound_ctrl:1
	v_pk_fma_f32 v[14:15], v[90:91], v[20:21], v[14:15]
	ds_read_b128 v[72:75], v26 offset:4096
	v_pk_fma_f32 v[14:15], v[92:93], v[22:23], v[14:15]
	ds_read_b128 v[76:79], v26 offset:4112
	v_pk_fma_f32 v[14:15], v[94:95], v[24:25], v[14:15]
	ds_read_b128 v[88:91], v26 offset:4608
	v_add_f32_e32 v101, v14, v15
	ds_read_b128 v[92:95], v26 offset:4624
	v_add_f32_dpp v100, v100, v100 row_half_mirror row_mask:0xf bank_mask:0x5
	ds_read_b128 v[28:31], v26 offset:5120
	ds_read_b128 v[32:35], v26 offset:5136
	s_waitcnt lgkmcnt(9)
	v_pk_fma_f32 v[18:19], v[36:37], v[8:9], v[116:117] op_sel_hi:[1,0,1]
	v_pk_fma_f32 v[20:21], v[38:39], v[8:9], v[118:119] op_sel_hi:[1,0,1]
	v_pk_mul_f32 v[10:11], v[18:19], v[64:65]
	v_pk_fma_f32 v[22:23], v[40:41], v[8:9], v[120:121] op_sel_hi:[1,0,1]
	v_pk_fma_f32 v[10:11], v[20:21], v[66:67], v[10:11]
	v_pk_fma_f32 v[24:25], v[42:43], v[8:9], v[122:123] op_sel_hi:[1,0,1]
	v_pk_fma_f32 v[10:11], v[22:23], v[68:69], v[10:11]
	ds_read_b128 v[44:47], v26 offset:5632
	v_pk_fma_f32 v[10:11], v[24:25], v[70:71], v[10:11]
	ds_read_b128 v[48:51], v26 offset:5648
	v_add_f32_e32 v10, v10, v11
	ds_read_b32 v60, v27 offset:6144
	s_waitcnt lgkmcnt(9)
	v_pk_fma_f32 v[116:117], v[96:97], v[80:81], v[18:19] op_sel_hi:[0,1,1]
	v_add_f32_dpp v10, v10, v10 quad_perm:[1,0,3,2] row_mask:0xf bank_mask:0xf bound_ctrl:1
	v_pk_fma_f32 v[118:119], v[96:97], v[82:83], v[20:21] op_sel_hi:[0,1,1]
	v_pk_fma_f32 v[120:121], v[96:97], v[84:85], v[22:23] op_sel_hi:[0,1,1]
	v_add_f32_dpp v10, v10, v10 quad_perm:[2,3,0,1] row_mask:0xf bank_mask:0xf bound_ctrl:1
	v_pk_fma_f32 v[122:123], v[96:97], v[86:87], v[24:25] op_sel_hi:[0,1,1]
	v_pk_mul_f32 v[12:13], v[52:53], v[18:19]
	v_add_f32_dpp v10, v10, v10 row_half_mirror row_mask:0xf bank_mask:0xf bound_ctrl:1
	v_pk_fma_f32 v[12:13], v[54:55], v[20:21], v[12:13]
	ds_read_b128 v[36:39], v26 offset:5376
	v_pk_fma_f32 v[12:13], v[56:57], v[22:23], v[12:13]
	ds_read_b128 v[40:43], v26 offset:5392
	v_pk_fma_f32 v[12:13], v[58:59], v[24:25], v[12:13]
	ds_read_b128 v[52:55], v26 offset:5888
	v_add_f32_e32 v102, v12, v13
	ds_read_b128 v[56:59], v26 offset:5904
	v_add_f32_dpp v101, v101, v101 row_half_mirror row_mask:0xf bank_mask:0x5
	ds_read_b128 v[64:67], v26 offset:6400
	ds_read_b128 v[68:71], v26 offset:6416
	s_waitcnt lgkmcnt(9)
	v_pk_fma_f32 v[18:19], v[72:73], v[10:11], v[116:117] op_sel_hi:[1,0,1]
	v_pk_fma_f32 v[20:21], v[74:75], v[10:11], v[118:119] op_sel_hi:[1,0,1]
	v_pk_mul_f32 v[8:9], v[18:19], v[28:29]
	v_pk_fma_f32 v[22:23], v[76:77], v[10:11], v[120:121] op_sel_hi:[1,0,1]
	v_pk_fma_f32 v[8:9], v[20:21], v[30:31], v[8:9]
	v_pk_fma_f32 v[24:25], v[78:79], v[10:11], v[122:123] op_sel_hi:[1,0,1]
	v_pk_fma_f32 v[8:9], v[22:23], v[32:33], v[8:9]
	ds_read_b128 v[80:83], v26 offset:6912
	v_pk_fma_f32 v[8:9], v[24:25], v[34:35], v[8:9]
	ds_read_b128 v[84:87], v26 offset:6928
	v_add_f32_e32 v8, v8, v9
	ds_read_b32 v96, v27 offset:7424
	s_waitcnt lgkmcnt(9)
	v_pk_fma_f32 v[116:117], v[60:61], v[44:45], v[18:19] op_sel_hi:[0,1,1]
	v_add_f32_dpp v8, v8, v8 quad_perm:[1,0,3,2] row_mask:0xf bank_mask:0xf bound_ctrl:1
	v_pk_fma_f32 v[118:119], v[60:61], v[46:47], v[20:21] op_sel_hi:[0,1,1]
	v_pk_fma_f32 v[120:121], v[60:61], v[48:49], v[22:23] op_sel_hi:[0,1,1]
	v_add_f32_dpp v8, v8, v8 quad_perm:[2,3,0,1] row_mask:0xf bank_mask:0xf bound_ctrl:1
	v_pk_fma_f32 v[122:123], v[60:61], v[50:51], v[24:25] op_sel_hi:[0,1,1]
	v_pk_mul_f32 v[14:15], v[88:89], v[18:19]
	v_add_f32_dpp v8, v8, v8 row_half_mirror row_mask:0xf bank_mask:0xf bound_ctrl:1
	v_pk_fma_f32 v[14:15], v[90:91], v[20:21], v[14:15]
	ds_read_b128 v[72:75], v26 offset:6656
	v_pk_fma_f32 v[14:15], v[92:93], v[22:23], v[14:15]
	ds_read_b128 v[76:79], v26 offset:6672
	v_pk_fma_f32 v[14:15], v[94:95], v[24:25], v[14:15]
	ds_read_b128 v[88:91], v26 offset:7168
	v_add_f32_e32 v103, v14, v15
	ds_read_b128 v[92:95], v26 offset:7184
	v_add_f32_dpp v102, v102, v102 row_half_mirror row_mask:0xf bank_mask:0x5
	ds_read_b128 v[28:31], v26 offset:7680
	ds_read_b128 v[32:35], v26 offset:7696
	s_waitcnt lgkmcnt(9)
	v_pk_fma_f32 v[18:19], v[36:37], v[8:9], v[116:117] op_sel_hi:[1,0,1]
	v_pk_fma_f32 v[20:21], v[38:39], v[8:9], v[118:119] op_sel_hi:[1,0,1]
	v_pk_mul_f32 v[10:11], v[18:19], v[64:65]
	v_pk_fma_f32 v[22:23], v[40:41], v[8:9], v[120:121] op_sel_hi:[1,0,1]
	v_pk_fma_f32 v[10:11], v[20:21], v[66:67], v[10:11]
	v_pk_fma_f32 v[24:25], v[42:43], v[8:9], v[122:123] op_sel_hi:[1,0,1]
	v_pk_fma_f32 v[10:11], v[22:23], v[68:69], v[10:11]
	ds_read_b128 v[44:47], v26 offset:8192
	v_pk_fma_f32 v[10:11], v[24:25], v[70:71], v[10:11]
	ds_read_b128 v[48:51], v26 offset:8208
	v_add_f32_e32 v10, v10, v11
	ds_read_b32 v60, v27 offset:8704
	s_waitcnt lgkmcnt(9)
; #define LAS __attribute__((address_space(3)))
; __device__ __forceinline__ float sum8(float x) { x += dppf<0xB1>(x); x += dppf<0x4E>(x); x += dppf<0x141>(x); return x; }
; __global__ void __launch_bounds__(512, 2) fwd_megakernel(Params P) {
;     ...
;                             for (int tt = 0; tt < 32; tt += 8) {
;                                 float yk = 0.f;
;                                 const f32x4 ge0 = *(const LAS f32x4*)(pk + 40960 + (tt >> 3) * 256), ge1 = *(const LAS f32x4*)(pk + 40960 + (tt >> 3) * 256 + 16);
; #pragma unroll
;                                 for (int j = 0; j < 8; ++j) {
;                                     if (j < 7 || tt + 8 < 32) SCAN_LOAD(rg2[(j + 1) & 1], rv2[(j + 1) & 1], tt + j + 1);
;                                     __builtin_amdgcn_sched_barrier(0);
;                                     const f32x4 (&cur)[8] = rg2[j & 1]; const float curv = rv2[j & 1];
;                                     const f32x2 v2 = {curv, curv};
;                                     const f32x2 pa = v2 * cur[4].xy + Sa, pb = v2 * cur[4].zw + Sb, pc = v2 * cur[5].xy + Sc, pd = v2 * cur[5].zw + Sd;
;                                     f32x2 t0 = Sa * cur[0].xy; t0 = Sb * cur[0].zw + t0;
;                                     f32x2 t1 = Sc * cur[1].xy; t1 = Sd * cur[1].zw + t1;
;                                     const f32x2 t = t0 + t1;
;                                     float sa = sum8(t.x + t.y);
;                                     const f32x2 sa2 = {sa, sa};
;                                     Sa = sa2 * cur[2].xy + pa; Sb = sa2 * cur[2].zw + pb; Sc = sa2 * cur[3].xy + pc; Sd = sa2 * cur[3].zw + pd;
;                                     f32x2 u0 = Sa * cur[6].xy; u0 = Sb * cur[6].zw + u0;
;                                     f32x2 u1 = Sc * cur[7].xy; u1 = Sd * cur[7].zw + u1;
;                                     const f32x2 u = u0 + u1;
;                                     const float y = sum8(u.x + u.y);
;                                     yk = (kq == j) ? y : yk;
;                                 }
;                                 Sa *= ge0.xy; Sb *= ge0.zw; Sc *= ge1.xy; Sd *= ge1.zw;
;                                 yout[(size_t)(c * 32 + tt + kq) * 1024] = (f16)yk;
	v_pk_fma_f32 v[116:117], v[96:97], v[80:81], v[18:19] op_sel_hi:[0,1,1]
	v_add_f32_dpp v10, v10, v10 quad_perm:[1,0,3,2] row_mask:0xf bank_mask:0xf bound_ctrl:1
	v_pk_fma_f32 v[118:119], v[96:97], v[82:83], v[20:21] op_sel_hi:[0,1,1]
	v_pk_fma_f32 v[120:121], v[96:97], v[84:85], v[22:23] op_sel_hi:[0,1,1]
	v_add_f32_dpp v10, v10, v10 quad_perm:[2,3,0,1] row_mask:0xf bank_mask:0xf bound_ctrl:1
	v_pk_fma_f32 v[122:123], v[96:97], v[86:87], v[24:25] op_sel_hi:[0,1,1]
	v_pk_mul_f32 v[12:13], v[52:53], v[18:19]
	v_add_f32_dpp v10, v10, v10 row_half_mirror row_mask:0xf bank_mask:0xf bound_ctrl:1
	v_pk_fma_f32 v[12:13], v[54:55], v[20:21], v[12:13]
	ds_read_b128 v[36:39], v26 offset:7936
	v_pk_fma_f32 v[12:13], v[56:57], v[22:23], v[12:13]
	ds_read_b128 v[40:43], v26 offset:7952
	v_pk_fma_f32 v[12:13], v[58:59], v[24:25], v[12:13]
	ds_read_b128 v[52:55], v26 offset:8448
	v_add_f32_e32 v104, v12, v13
	ds_read_b128 v[56:59], v26 offset:8464
	v_add_f32_dpp v103, v103, v103 row_half_mirror row_mask:0xf bank_mask:0x5
	v_add_f32_dpp v100, v104, v104 row_half_mirror row_mask:0xf bank_mask:0xa
	ds_read_b128 v[64:67], v26 offset:8960
	ds_read_b128 v[68:71], v26 offset:8976
	s_waitcnt lgkmcnt(9)
	v_pk_fma_f32 v[18:19], v[72:73], v[10:11], v[116:117] op_sel_hi:[1,0,1]
	v_pk_fma_f32 v[20:21], v[74:75], v[10:11], v[118:119] op_sel_hi:[1,0,1]
	v_pk_mul_f32 v[8:9], v[18:19], v[28:29]
	v_pk_fma_f32 v[22:23], v[76:77], v[10:11], v[120:121] op_sel_hi:[1,0,1]
	v_pk_fma_f32 v[8:9], v[20:21], v[30:31], v[8:9]
	v_pk_fma_f32 v[24:25], v[78:79], v[10:11], v[122:123] op_sel_hi:[1,0,1]
	v_pk_fma_f32 v[8:9], v[22:23], v[32:33], v[8:9]
	ds_read_b128 v[80:83], v26 offset:9472
	v_pk_fma_f32 v[8:9], v[24:25], v[34:35], v[8:9]
	ds_read_b128 v[84:87], v26 offset:9488
	v_add_f32_e32 v8, v8, v9
	ds_read_b32 v96, v27 offset:9984
	s_waitcnt lgkmcnt(9)
	v_pk_fma_f32 v[116:117], v[60:61], v[44:45], v[18:19] op_sel_hi:[0,1,1]
	v_add_f32_dpp v8, v8, v8 quad_perm:[1,0,3,2] row_mask:0xf bank_mask:0xf bound_ctrl:1
	v_pk_fma_f32 v[118:119], v[60:61], v[46:47], v[20:21] op_sel_hi:[0,1,1]
	v_pk_fma_f32 v[120:121], v[60:61], v[48:49], v[22:23] op_sel_hi:[0,1,1]
	v_add_f32_dpp v8, v8, v8 quad_perm:[2,3,0,1] row_mask:0xf bank_mask:0xf bound_ctrl:1
	v_pk_fma_f32 v[122:123], v[60:61], v[50:51], v[24:25] op_sel_hi:[0,1,1]
	v_pk_mul_f32 v[14:15], v[88:89], v[18:19]
	v_add_f32_dpp v8, v8, v8 row_half_mirror row_mask:0xf bank_mask:0xf bound_ctrl:1
	v_pk_fma_f32 v[14:15], v[90:91], v[20:21], v[14:15]
	ds_read_b128 v[72:75], v26 offset:9216
	v_pk_fma_f32 v[14:15], v[92:93], v[22:23], v[14:15]
	ds_read_b128 v[76:79], v26 offset:9232
	v_pk_fma_f32 v[14:15], v[94:95], v[24:25], v[14:15]
	ds_read_b128 v[88:91], v26 offset:9728
	v_add_f32_e32 v105, v14, v15
	ds_read_b128 v[92:95], v26 offset:9744
	ds_read_b128 v[28:31], v26 offset:10240
	v_add_f32_dpp v101, v105, v105 row_half_mirror row_mask:0xf bank_mask:0xa
	ds_read_b128 v[32:35], v26 offset:10256
	s_waitcnt lgkmcnt(9)
	v_pk_fma_f32 v[18:19], v[36:37], v[8:9], v[116:117] op_sel_hi:[1,0,1]
	v_pk_fma_f32 v[20:21], v[38:39], v[8:9], v[118:119] op_sel_hi:[1,0,1]
	v_pk_mul_f32 v[10:11], v[18:19], v[64:65]
	v_pk_fma_f32 v[22:23], v[40:41], v[8:9], v[120:121] op_sel_hi:[1,0,1]
	v_pk_fma_f32 v[10:11], v[20:21], v[66:67], v[10:11]
	v_pk_fma_f32 v[24:25], v[42:43], v[8:9], v[122:123] op_sel_hi:[1,0,1]
	v_pk_fma_f32 v[10:11], v[22:23], v[68:69], v[10:11]
	ds_read_b128 v[44:47], v26 offset:10752
	v_pk_fma_f32 v[10:11], v[24:25], v[70:71], v[10:11]
	ds_read_b128 v[48:51], v26 offset:10768
	v_add_f32_e32 v10, v10, v11
	ds_read_b32 v60, v27 offset:11264
	s_waitcnt lgkmcnt(9)
	v_pk_fma_f32 v[116:117], v[96:97], v[80:81], v[18:19] op_sel_hi:[0,1,1]
	v_add_f32_dpp v10, v10, v10 quad_perm:[1,0,3,2] row_mask:0xf bank_mask:0xf bound_ctrl:1
	v_pk_fma_f32 v[118:119], v[96:97], v[82:83], v[20:21] op_sel_hi:[0,1,1]
	v_pk_fma_f32 v[120:121], v[96:97], v[84:85], v[22:23] op_sel_hi:[0,1,1]
	v_add_f32_dpp v10, v10, v10 quad_perm:[2,3,0,1] row_mask:0xf bank_mask:0xf bound_ctrl:1
	v_pk_fma_f32 v[122:123], v[96:97], v[86:87], v[24:25] op_sel_hi:[0,1,1]
	v_pk_mul_f32 v[12:13], v[52:53], v[18:19]
	v_add_f32_dpp v10, v10, v10 row_half_mirror row_mask:0xf bank_mask:0xf bound_ctrl:1
	v_pk_fma_f32 v[12:13], v[54:55], v[20:21], v[12:13]
	ds_read_b128 v[36:39], v26 offset:10496
	v_pk_fma_f32 v[12:13], v[56:57], v[22:23], v[12:13]
	ds_read_b128 v[40:43], v26 offset:10512
	v_pk_fma_f32 v[12:13], v[58:59], v[24:25], v[12:13]
	ds_read_b128 v[52:55], v26 offset:11008
	v_add_f32_e32 v106, v12, v13
	ds_read_b128 v[56:59], v26 offset:11024
	ds_read_b128 v[64:67], v26 offset:11520
	v_add_f32_dpp v102, v106, v106 row_half_mirror row_mask:0xf bank_mask:0xa
	ds_read_b128 v[68:71], v26 offset:11536
	s_waitcnt lgkmcnt(9)
	v_pk_fma_f32 v[18:19], v[72:73], v[10:11], v[116:117] op_sel_hi:[1,0,1]
	v_pk_fma_f32 v[20:21], v[74:75], v[10:11], v[118:119] op_sel_hi:[1,0,1]
	v_pk_fma_f32 v[22:23], v[76:77], v[10:11], v[120:121] op_sel_hi:[1,0,1]
	v_pk_fma_f32 v[24:25], v[78:79], v[10:11], v[122:123] op_sel_hi:[1,0,1]
	v_pk_mul_f32 v[108:109], v[124:125], v[18:19]
	v_pk_mul_f32 v[110:111], v[126:127], v[20:21]
	v_pk_mul_f32 v[8:9], v[108:109], v[28:29]
	v_pk_mul_f32 v[112:113], v[128:129], v[22:23]
	v_pk_fma_f32 v[8:9], v[110:111], v[30:31], v[8:9]
	v_pk_mul_f32 v[114:115], v[130:131], v[24:25]
	v_pk_fma_f32 v[8:9], v[112:113], v[32:33], v[8:9]
	ds_read_b128 v[80:83], v26 offset:12032
	v_pk_fma_f32 v[8:9], v[114:115], v[34:35], v[8:9]
	ds_read_b128 v[84:87], v26 offset:12048
	v_add_f32_e32 v8, v8, v9
	ds_read_b32 v96, v27 offset:12544
	s_waitcnt lgkmcnt(9)
; #define LAS __attribute__((address_space(3)))
; __device__ __forceinline__ float sum8(float x) { x += dppf<0xB1>(x); x += dppf<0x4E>(x); x += dppf<0x141>(x); return x; }
; __global__ void __launch_bounds__(512, 2) fwd_megakernel(Params P) {
;     ...
;                             for (int tt = 0; tt < 32; tt += 8) {
;                                 float yk = 0.f;
;                                 const f32x4 ge0 = *(const LAS f32x4*)(pk + 40960 + (tt >> 3) * 256), ge1 = *(const LAS f32x4*)(pk + 40960 + (tt >> 3) * 256 + 16);
; #pragma unroll
;                                 for (int j = 0; j < 8; ++j) {
;                                     if (j < 7 || tt + 8 < 32) SCAN_LOAD(rg2[(j + 1) & 1], rv2[(j + 1) & 1], tt + j + 1);
;                                     __builtin_amdgcn_sched_barrier(0);
;                                     const f32x4 (&cur)[8] = rg2[j & 1]; const float curv = rv2[j & 1];
;                                     const f32x2 v2 = {curv, curv};
;                                     const f32x2 pa = v2 * cur[4].xy + Sa, pb = v2 * cur[4].zw + Sb, pc = v2 * cur[5].xy + Sc, pd = v2 * cur[5].zw + Sd;
;                                     f32x2 t0 = Sa * cur[0].xy; t0 = Sb * cur[0].zw + t0;
;                                     f32x2 t1 = Sc * cur[1].xy; t1 = Sd * cur[1].zw + t1;
;                                     const f32x2 t = t0 + t1;
;                                     float sa = sum8(t.x + t.y);
;                                     const f32x2 sa2 = {sa, sa};
;                                     Sa = sa2 * cur[2].xy + pa; Sb = sa2 * cur[2].zw + pb; Sc = sa2 * cur[3].xy + pc; Sd = sa2 * cur[3].zw + pd;
;                                     f32x2 u0 = Sa * cur[6].xy; u0 = Sb * cur[6].zw + u0;
;                                     f32x2 u1 = Sc * cur[7].xy; u1 = Sd * cur[7].zw + u1;
;                                     const f32x2 u = u0 + u1;
;                                     const float y = sum8(u.x + u.y);
;                                     yk = (kq == j) ? y : yk;
;                                 }
;                                 Sa *= ge0.xy; Sb *= ge0.zw; Sc *= ge1.xy; Sd *= ge1.zw;
;                                 yout[(size_t)(c * 32 + tt + kq) * 1024] = (f16)yk;
	v_pk_fma_f32 v[116:117], v[60:61], v[44:45], v[108:109] op_sel_hi:[0,1,1]
	v_add_f32_dpp v8, v8, v8 quad_perm:[1,0,3,2] row_mask:0xf bank_mask:0xf bound_ctrl:1
	v_pk_fma_f32 v[118:119], v[60:61], v[46:47], v[110:111] op_sel_hi:[0,1,1]
	v_pk_fma_f32 v[120:121], v[60:61], v[48:49], v[112:113] op_sel_hi:[0,1,1]
	v_add_f32_dpp v8, v8, v8 quad_perm:[2,3,0,1] row_mask:0xf bank_mask:0xf bound_ctrl:1
	v_pk_fma_f32 v[122:123], v[60:61], v[50:51], v[114:115] op_sel_hi:[0,1,1]
	v_pk_mul_f32 v[14:15], v[88:89], v[18:19]
	v_add_f32_dpp v8, v8, v8 row_half_mirror row_mask:0xf bank_mask:0xf bound_ctrl:1
	v_pk_fma_f32 v[14:15], v[90:91], v[20:21], v[14:15]
	ds_read_b128 v[72:75], v26 offset:11776
	v_pk_fma_f32 v[14:15], v[92:93], v[22:23], v[14:15]
	ds_read_b128 v[76:79], v26 offset:11792
	v_pk_fma_f32 v[14:15], v[94:95], v[24:25], v[14:15]
	ds_read_b128 v[88:91], v26 offset:12288
	v_add_f32_e32 v107, v14, v15
	ds_read_b128 v[92:95], v26 offset:12304
	v_add_f32_dpp v16, v100, v100 quad_perm:[2,3,0,1] row_mask:0xf bank_mask:0xf bound_ctrl:1
	v_add_f32_dpp v103, v107, v107 row_half_mirror row_mask:0xf bank_mask:0xa
	v_add_f32_dpp v62, v101, v101 quad_perm:[2,3,0,1] row_mask:0xf bank_mask:0xf bound_ctrl:1
	v_add_f32_dpp v17, v102, v102 quad_perm:[2,3,0,1] row_mask:0xf bank_mask:0xf bound_ctrl:1
	v_add_f32_dpp v63, v103, v103 quad_perm:[2,3,0,1] row_mask:0xf bank_mask:0xf bound_ctrl:1
	v_cndmask_b32_e64 v61, v16, v17, s[100:101]
	v_cndmask_b32_e64 v97, v62, v63, s[100:101]
	ds_read_b128 v[28:31], v26 offset:12800
	v_add_f32_dpp v16, v61, v61 quad_perm:[1,0,3,2] row_mask:0xf bank_mask:0xf bound_ctrl:1
	v_add_f32_dpp v17, v97, v97 quad_perm:[1,0,3,2] row_mask:0xf bank_mask:0xf bound_ctrl:1
	ds_read_b128 v[32:35], v26 offset:12816
	v_cndmask_b32_e64 v16, v16, v17, s[44:45]
	s_waitcnt lgkmcnt(6)
	v_pk_fma_f32 v[108:109], v[36:37], v[8:9], v[116:117] op_sel_hi:[1,0,1]
	v_cvt_f16_f32_e32 v17, v16
	v_pk_fma_f32 v[110:111], v[38:39], v[8:9], v[118:119] op_sel_hi:[1,0,1]
	global_store_short v[98:99], v17, off
	v_pk_mul_f32 v[10:11], v[108:109], v[64:65]
	v_add_co_u32_e32 v98, vcc, 0x4000, v98
	v_pk_fma_f32 v[112:113], v[40:41], v[8:9], v[120:121] op_sel_hi:[1,0,1]
	v_pk_fma_f32 v[10:11], v[110:111], v[66:67], v[10:11]
	v_addc_co_u32_e32 v99, vcc, 0, v99, vcc
	v_pk_fma_f32 v[114:115], v[42:43], v[8:9], v[122:123] op_sel_hi:[1,0,1]
	v_pk_fma_f32 v[10:11], v[112:113], v[68:69], v[10:11]
	ds_read_b128 v[44:47], v26 offset:13312
	v_pk_fma_f32 v[10:11], v[114:115], v[70:71], v[10:11]
	ds_read_b128 v[48:51], v26 offset:13328
	v_add_f32_e32 v10, v10, v11
	ds_read_b32 v60, v27 offset:13824
	v_pk_fma_f32 v[116:117], v[96:97], v[80:81], v[108:109] op_sel_hi:[0,1,1]
	v_add_f32_dpp v10, v10, v10 quad_perm:[1,0,3,2] row_mask:0xf bank_mask:0xf bound_ctrl:1
	v_pk_fma_f32 v[118:119], v[96:97], v[82:83], v[110:111] op_sel_hi:[0,1,1]
	v_pk_fma_f32 v[120:121], v[96:97], v[84:85], v[112:113] op_sel_hi:[0,1,1]
	v_add_f32_dpp v10, v10, v10 quad_perm:[2,3,0,1] row_mask:0xf bank_mask:0xf bound_ctrl:1
	v_pk_fma_f32 v[122:123], v[96:97], v[86:87], v[114:115] op_sel_hi:[0,1,1]
	v_pk_mul_f32 v[12:13], v[52:53], v[108:109]
	v_add_f32_dpp v10, v10, v10 row_half_mirror row_mask:0xf bank_mask:0xf bound_ctrl:1
	v_pk_fma_f32 v[12:13], v[54:55], v[110:111], v[12:13]
	ds_read_b128 v[36:39], v26 offset:13056
	v_pk_fma_f32 v[12:13], v[56:57], v[112:113], v[12:13]
	ds_read_b128 v[40:43], v26 offset:13072
	v_pk_fma_f32 v[12:13], v[58:59], v[114:115], v[12:13]
	ds_read_b128 v[52:55], v26 offset:13568
	v_add_f32_e32 v100, v12, v13
	ds_read_b128 v[56:59], v26 offset:13584
	ds_read_b128 v[124:127], v26 offset:41216
	ds_read_b128 v[128:131], v26 offset:41232
	ds_read_b128 v[64:67], v26 offset:14080
	ds_read_b128 v[68:71], v26 offset:14096
	s_waitcnt lgkmcnt(11)
	v_pk_fma_f32 v[108:109], v[72:73], v[10:11], v[116:117] op_sel_hi:[1,0,1]
	v_pk_fma_f32 v[110:111], v[74:75], v[10:11], v[118:119] op_sel_hi:[1,0,1]
	v_pk_mul_f32 v[8:9], v[108:109], v[28:29]
	v_pk_fma_f32 v[112:113], v[76:77], v[10:11], v[120:121] op_sel_hi:[1,0,1]
	v_pk_fma_f32 v[8:9], v[110:111], v[30:31], v[8:9]
	v_pk_fma_f32 v[114:115], v[78:79], v[10:11], v[122:123] op_sel_hi:[1,0,1]
	v_pk_fma_f32 v[8:9], v[112:113], v[32:33], v[8:9]
	ds_read_b128 v[80:83], v26 offset:14592
	v_pk_fma_f32 v[8:9], v[114:115], v[34:35], v[8:9]
	ds_read_b128 v[84:87], v26 offset:14608
	v_add_f32_e32 v8, v8, v9
	ds_read_b32 v96, v27 offset:15104
	s_waitcnt lgkmcnt(11)
	v_pk_fma_f32 v[116:117], v[60:61], v[44:45], v[108:109] op_sel_hi:[0,1,1]
	v_add_f32_dpp v8, v8, v8 quad_perm:[1,0,3,2] row_mask:0xf bank_mask:0xf bound_ctrl:1
	v_pk_fma_f32 v[118:119], v[60:61], v[46:47], v[110:111] op_sel_hi:[0,1,1]
	v_pk_fma_f32 v[120:121], v[60:61], v[48:49], v[112:113] op_sel_hi:[0,1,1]
	v_add_f32_dpp v8, v8, v8 quad_perm:[2,3,0,1] row_mask:0xf bank_mask:0xf bound_ctrl:1
	v_pk_fma_f32 v[122:123], v[60:61], v[50:51], v[114:115] op_sel_hi:[0,1,1]
	v_pk_mul_f32 v[14:15], v[88:89], v[108:109]
	v_add_f32_dpp v8, v8, v8 row_half_mirror row_mask:0xf bank_mask:0xf bound_ctrl:1
	v_pk_fma_f32 v[14:15], v[90:91], v[110:111], v[14:15]
	ds_read_b128 v[72:75], v26 offset:14336
	v_pk_fma_f32 v[14:15], v[92:93], v[112:113], v[14:15]
	ds_read_b128 v[76:79], v26 offset:14352
	v_pk_fma_f32 v[14:15], v[94:95], v[114:115], v[14:15]
	ds_read_b128 v[88:91], v26 offset:14848
	v_add_f32_e32 v101, v14, v15
	ds_read_b128 v[92:95], v26 offset:14864
	v_add_f32_dpp v100, v100, v100 row_half_mirror row_mask:0xf bank_mask:0x5
	ds_read_b128 v[28:31], v26 offset:15360
	ds_read_b128 v[32:35], v26 offset:15376
	s_waitcnt lgkmcnt(9)
; #define LAS __attribute__((address_space(3)))
; __device__ __forceinline__ float sum8(float x) { x += dppf<0xB1>(x); x += dppf<0x4E>(x); x += dppf<0x141>(x); return x; }
; __global__ void __launch_bounds__(512, 2) fwd_megakernel(Params P) {
;     ...
;                             for (int tt = 0; tt < 32; tt += 8) {
;                                 float yk = 0.f;
;                                 const f32x4 ge0 = *(const LAS f32x4*)(pk + 40960 + (tt >> 3) * 256), ge1 = *(const LAS f32x4*)(pk + 40960 + (tt >> 3) * 256 + 16);
; #pragma unroll
;                                 for (int j = 0; j < 8; ++j) {
;                                     if (j < 7 || tt + 8 < 32) SCAN_LOAD(rg2[(j + 1) & 1], rv2[(j + 1) & 1], tt + j + 1);
;                                     __builtin_amdgcn_sched_barrier(0);
;                                     const f32x4 (&cur)[8] = rg2[j & 1]; const float curv = rv2[j & 1];
;                                     const f32x2 v2 = {curv, curv};
;                                     const f32x2 pa = v2 * cur[4].xy + Sa, pb = v2 * cur[4].zw + Sb, pc = v2 * cur[5].xy + Sc, pd = v2 * cur[5].zw + Sd;
;                                     f32x2 t0 = Sa * cur[0].xy; t0 = Sb * cur[0].zw + t0;
;                                     f32x2 t1 = Sc * cur[1].xy; t1 = Sd * cur[1].zw + t1;
;                                     const f32x2 t = t0 + t1;
;                                     float sa = sum8(t.x + t.y);
;                                     const f32x2 sa2 = {sa, sa};
;                                     Sa = sa2 * cur[2].xy + pa; Sb = sa2 * cur[2].zw + pb; Sc = sa2 * cur[3].xy + pc; Sd = sa2 * cur[3].zw + pd;
;                                     f32x2 u0 = Sa * cur[6].xy; u0 = Sb * cur[6].zw + u0;
;                                     f32x2 u1 = Sc * cur[7].xy; u1 = Sd * cur[7].zw + u1;
;                                     const f32x2 u = u0 + u1;
;                                     const float y = sum8(u.x + u.y);
;                                     yk = (kq == j) ? y : yk;
;                                 }
;                                 Sa *= ge0.xy; Sb *= ge0.zw; Sc *= ge1.xy; Sd *= ge1.zw;
;                                 yout[(size_t)(c * 32 + tt + kq) * 1024] = (f16)yk;
	v_pk_fma_f32 v[108:109], v[36:37], v[8:9], v[116:117] op_sel_hi:[1,0,1]
	v_pk_fma_f32 v[110:111], v[38:39], v[8:9], v[118:119] op_sel_hi:[1,0,1]
	v_pk_mul_f32 v[10:11], v[108:109], v[64:65]
	v_pk_fma_f32 v[112:113], v[40:41], v[8:9], v[120:121] op_sel_hi:[1,0,1]
	v_pk_fma_f32 v[10:11], v[110:111], v[66:67], v[10:11]
	v_pk_fma_f32 v[114:115], v[42:43], v[8:9], v[122:123] op_sel_hi:[1,0,1]
	v_pk_fma_f32 v[10:11], v[112:113], v[68:69], v[10:11]
	ds_read_b128 v[44:47], v26 offset:15872
	v_pk_fma_f32 v[10:11], v[114:115], v[70:71], v[10:11]
	ds_read_b128 v[48:51], v26 offset:15888
	v_add_f32_e32 v10, v10, v11
	ds_read_b32 v60, v27 offset:16384
	s_waitcnt lgkmcnt(9)
	v_pk_fma_f32 v[116:117], v[96:97], v[80:81], v[108:109] op_sel_hi:[0,1,1]
	v_add_f32_dpp v10, v10, v10 quad_perm:[1,0,3,2] row_mask:0xf bank_mask:0xf bound_ctrl:1
	v_pk_fma_f32 v[118:119], v[96:97], v[82:83], v[110:111] op_sel_hi:[0,1,1]
	v_pk_fma_f32 v[120:121], v[96:97], v[84:85], v[112:113] op_sel_hi:[0,1,1]
	v_add_f32_dpp v10, v10, v10 quad_perm:[2,3,0,1] row_mask:0xf bank_mask:0xf bound_ctrl:1
	v_pk_fma_f32 v[122:123], v[96:97], v[86:87], v[114:115] op_sel_hi:[0,1,1]
	v_pk_mul_f32 v[12:13], v[52:53], v[108:109]
	v_add_f32_dpp v10, v10, v10 row_half_mirror row_mask:0xf bank_mask:0xf bound_ctrl:1
	v_pk_fma_f32 v[12:13], v[54:55], v[110:111], v[12:13]
	ds_read_b128 v[36:39], v26 offset:15616
	v_pk_fma_f32 v[12:13], v[56:57], v[112:113], v[12:13]
	ds_read_b128 v[40:43], v26 offset:15632
	v_pk_fma_f32 v[12:13], v[58:59], v[114:115], v[12:13]
	ds_read_b128 v[52:55], v26 offset:16128
	v_add_f32_e32 v102, v12, v13
	ds_read_b128 v[56:59], v26 offset:16144
	v_add_f32_dpp v101, v101, v101 row_half_mirror row_mask:0xf bank_mask:0x5
	ds_read_b128 v[64:67], v26 offset:16640
	ds_read_b128 v[68:71], v26 offset:16656
	s_waitcnt lgkmcnt(9)
	v_pk_fma_f32 v[108:109], v[72:73], v[10:11], v[116:117] op_sel_hi:[1,0,1]
	v_pk_fma_f32 v[110:111], v[74:75], v[10:11], v[118:119] op_sel_hi:[1,0,1]
	v_pk_mul_f32 v[8:9], v[108:109], v[28:29]
	v_pk_fma_f32 v[112:113], v[76:77], v[10:11], v[120:121] op_sel_hi:[1,0,1]
	v_pk_fma_f32 v[8:9], v[110:111], v[30:31], v[8:9]
	v_pk_fma_f32 v[114:115], v[78:79], v[10:11], v[122:123] op_sel_hi:[1,0,1]
	v_pk_fma_f32 v[8:9], v[112:113], v[32:33], v[8:9]
	ds_read_b128 v[80:83], v26 offset:17152
	v_pk_fma_f32 v[8:9], v[114:115], v[34:35], v[8:9]
	ds_read_b128 v[84:87], v26 offset:17168
	v_add_f32_e32 v8, v8, v9
	ds_read_b32 v96, v27 offset:17664
	s_waitcnt lgkmcnt(9)
	v_pk_fma_f32 v[116:117], v[60:61], v[44:45], v[108:109] op_sel_hi:[0,1,1]
	v_add_f32_dpp v8, v8, v8 quad_perm:[1,0,3,2] row_mask:0xf bank_mask:0xf bound_ctrl:1
	v_pk_fma_f32 v[118:119], v[60:61], v[46:47], v[110:111] op_sel_hi:[0,1,1]
	v_pk_fma_f32 v[120:121], v[60:61], v[48:49], v[112:113] op_sel_hi:[0,1,1]
	v_add_f32_dpp v8, v8, v8 quad_perm:[2,3,0,1] row_mask:0xf bank_mask:0xf bound_ctrl:1
	v_pk_fma_f32 v[122:123], v[60:61], v[50:51], v[114:115] op_sel_hi:[0,1,1]
	v_pk_mul_f32 v[14:15], v[88:89], v[108:109]
	v_add_f32_dpp v8, v8, v8 row_half_mirror row_mask:0xf bank_mask:0xf bound_ctrl:1
	v_pk_fma_f32 v[14:15], v[90:91], v[110:111], v[14:15]
	ds_read_b128 v[72:75], v26 offset:16896
	v_pk_fma_f32 v[14:15], v[92:93], v[112:113], v[14:15]
	ds_read_b128 v[76:79], v26 offset:16912
	v_pk_fma_f32 v[14:15], v[94:95], v[114:115], v[14:15]
	ds_read_b128 v[88:91], v26 offset:17408
	v_add_f32_e32 v103, v14, v15
	ds_read_b128 v[92:95], v26 offset:17424
	v_add_f32_dpp v102, v102, v102 row_half_mirror row_mask:0xf bank_mask:0x5
	ds_read_b128 v[28:31], v26 offset:17920
	ds_read_b128 v[32:35], v26 offset:17936
	s_waitcnt lgkmcnt(9)
	v_pk_fma_f32 v[108:109], v[36:37], v[8:9], v[116:117] op_sel_hi:[1,0,1]
	v_pk_fma_f32 v[110:111], v[38:39], v[8:9], v[118:119] op_sel_hi:[1,0,1]
	v_pk_mul_f32 v[10:11], v[108:109], v[64:65]
	v_pk_fma_f32 v[112:113], v[40:41], v[8:9], v[120:121] op_sel_hi:[1,0,1]
	v_pk_fma_f32 v[10:11], v[110:111], v[66:67], v[10:11]
	v_pk_fma_f32 v[114:115], v[42:43], v[8:9], v[122:123] op_sel_hi:[1,0,1]
	v_pk_fma_f32 v[10:11], v[112:113], v[68:69], v[10:11]
	ds_read_b128 v[44:47], v26 offset:18432
	v_pk_fma_f32 v[10:11], v[114:115], v[70:71], v[10:11]
	ds_read_b128 v[48:51], v26 offset:18448
	v_add_f32_e32 v10, v10, v11
	ds_read_b32 v60, v27 offset:18944
	s_waitcnt lgkmcnt(9)
	v_pk_fma_f32 v[116:117], v[96:97], v[80:81], v[108:109] op_sel_hi:[0,1,1]
	v_add_f32_dpp v10, v10, v10 quad_perm:[1,0,3,2] row_mask:0xf bank_mask:0xf bound_ctrl:1
	v_pk_fma_f32 v[118:119], v[96:97], v[82:83], v[110:111] op_sel_hi:[0,1,1]
	v_pk_fma_f32 v[120:121], v[96:97], v[84:85], v[112:113] op_sel_hi:[0,1,1]
	v_add_f32_dpp v10, v10, v10 quad_perm:[2,3,0,1] row_mask:0xf bank_mask:0xf bound_ctrl:1
	v_pk_fma_f32 v[122:123], v[96:97], v[86:87], v[114:115] op_sel_hi:[0,1,1]
	v_pk_mul_f32 v[12:13], v[52:53], v[108:109]
	v_add_f32_dpp v10, v10, v10 row_half_mirror row_mask:0xf bank_mask:0xf bound_ctrl:1
	v_pk_fma_f32 v[12:13], v[54:55], v[110:111], v[12:13]
	ds_read_b128 v[36:39], v26 offset:18176
	v_pk_fma_f32 v[12:13], v[56:57], v[112:113], v[12:13]
	ds_read_b128 v[40:43], v26 offset:18192
	v_pk_fma_f32 v[12:13], v[58:59], v[114:115], v[12:13]
	ds_read_b128 v[52:55], v26 offset:18688
	v_add_f32_e32 v104, v12, v13
	ds_read_b128 v[56:59], v26 offset:18704
	v_add_f32_dpp v103, v103, v103 row_half_mirror row_mask:0xf bank_mask:0x5
	v_add_f32_dpp v100, v104, v104 row_half_mirror row_mask:0xf bank_mask:0xa
	ds_read_b128 v[64:67], v26 offset:19200
	ds_read_b128 v[68:71], v26 offset:19216
	s_waitcnt lgkmcnt(9)
; #define LAS __attribute__((address_space(3)))
; __device__ __forceinline__ float sum8(float x) { x += dppf<0xB1>(x); x += dppf<0x4E>(x); x += dppf<0x141>(x); return x; }
; __global__ void __launch_bounds__(512, 2) fwd_megakernel(Params P) {
;     ...
;                             for (int tt = 0; tt < 32; tt += 8) {
;                                 float yk = 0.f;
;                                 const f32x4 ge0 = *(const LAS f32x4*)(pk + 40960 + (tt >> 3) * 256), ge1 = *(const LAS f32x4*)(pk + 40960 + (tt >> 3) * 256 + 16);
; #pragma unroll
;                                 for (int j = 0; j < 8; ++j) {
;                                     if (j < 7 || tt + 8 < 32) SCAN_LOAD(rg2[(j + 1) & 1], rv2[(j + 1) & 1], tt + j + 1);
;                                     __builtin_amdgcn_sched_barrier(0);
;                                     const f32x4 (&cur)[8] = rg2[j & 1]; const float curv = rv2[j & 1];
;                                     const f32x2 v2 = {curv, curv};
;                                     const f32x2 pa = v2 * cur[4].xy + Sa, pb = v2 * cur[4].zw + Sb, pc = v2 * cur[5].xy + Sc, pd = v2 * cur[5].zw + Sd;
;                                     f32x2 t0 = Sa * cur[0].xy; t0 = Sb * cur[0].zw + t0;
;                                     f32x2 t1 = Sc * cur[1].xy; t1 = Sd * cur[1].zw + t1;
;                                     const f32x2 t = t0 + t1;
;                                     float sa = sum8(t.x + t.y);
;                                     const f32x2 sa2 = {sa, sa};
;                                     Sa = sa2 * cur[2].xy + pa; Sb = sa2 * cur[2].zw + pb; Sc = sa2 * cur[3].xy + pc; Sd = sa2 * cur[3].zw + pd;
;                                     f32x2 u0 = Sa * cur[6].xy; u0 = Sb * cur[6].zw + u0;
;                                     f32x2 u1 = Sc * cur[7].xy; u1 = Sd * cur[7].zw + u1;
;                                     const f32x2 u = u0 + u1;
;                                     const float y = sum8(u.x + u.y);
;                                     yk = (kq == j) ? y : yk;
;                                 }
;                                 Sa *= ge0.xy; Sb *= ge0.zw; Sc *= ge1.xy; Sd *= ge1.zw;
;                                 yout[(size_t)(c * 32 + tt + kq) * 1024] = (f16)yk;
	v_pk_fma_f32 v[108:109], v[72:73], v[10:11], v[116:117] op_sel_hi:[1,0,1]
	v_pk_fma_f32 v[110:111], v[74:75], v[10:11], v[118:119] op_sel_hi:[1,0,1]
	v_pk_mul_f32 v[8:9], v[108:109], v[28:29]
	v_pk_fma_f32 v[112:113], v[76:77], v[10:11], v[120:121] op_sel_hi:[1,0,1]
	v_pk_fma_f32 v[8:9], v[110:111], v[30:31], v[8:9]
	v_pk_fma_f32 v[114:115], v[78:79], v[10:11], v[122:123] op_sel_hi:[1,0,1]
	v_pk_fma_f32 v[8:9], v[112:113], v[32:33], v[8:9]
	ds_read_b128 v[80:83], v26 offset:19712
	v_pk_fma_f32 v[8:9], v[114:115], v[34:35], v[8:9]
	ds_read_b128 v[84:87], v26 offset:19728
	v_add_f32_e32 v8, v8, v9
	ds_read_b32 v96, v27 offset:20224
	s_waitcnt lgkmcnt(9)
	v_pk_fma_f32 v[116:117], v[60:61], v[44:45], v[108:109] op_sel_hi:[0,1,1]
	v_add_f32_dpp v8, v8, v8 quad_perm:[1,0,3,2] row_mask:0xf bank_mask:0xf bound_ctrl:1
	v_pk_fma_f32 v[118:119], v[60:61], v[46:47], v[110:111] op_sel_hi:[0,1,1]
	v_pk_fma_f32 v[120:121], v[60:61], v[48:49], v[112:113] op_sel_hi:[0,1,1]
	v_add_f32_dpp v8, v8, v8 quad_perm:[2,3,0,1] row_mask:0xf bank_mask:0xf bound_ctrl:1
	v_pk_fma_f32 v[122:123], v[60:61], v[50:51], v[114:115] op_sel_hi:[0,1,1]
	v_pk_mul_f32 v[14:15], v[88:89], v[108:109]
	v_add_f32_dpp v8, v8, v8 row_half_mirror row_mask:0xf bank_mask:0xf bound_ctrl:1
	v_pk_fma_f32 v[14:15], v[90:91], v[110:111], v[14:15]
	ds_read_b128 v[72:75], v26 offset:19456
	v_pk_fma_f32 v[14:15], v[92:93], v[112:113], v[14:15]
	ds_read_b128 v[76:79], v26 offset:19472
	v_pk_fma_f32 v[14:15], v[94:95], v[114:115], v[14:15]
	ds_read_b128 v[88:91], v26 offset:19968
	v_add_f32_e32 v105, v14, v15
	ds_read_b128 v[92:95], v26 offset:19984
	ds_read_b128 v[28:31], v26 offset:20480
	v_add_f32_dpp v101, v105, v105 row_half_mirror row_mask:0xf bank_mask:0xa
	ds_read_b128 v[32:35], v26 offset:20496
	s_waitcnt lgkmcnt(9)
	v_pk_fma_f32 v[108:109], v[36:37], v[8:9], v[116:117] op_sel_hi:[1,0,1]
	v_pk_fma_f32 v[110:111], v[38:39], v[8:9], v[118:119] op_sel_hi:[1,0,1]
	v_pk_mul_f32 v[10:11], v[108:109], v[64:65]
	v_pk_fma_f32 v[112:113], v[40:41], v[8:9], v[120:121] op_sel_hi:[1,0,1]
	v_pk_fma_f32 v[10:11], v[110:111], v[66:67], v[10:11]
	v_pk_fma_f32 v[114:115], v[42:43], v[8:9], v[122:123] op_sel_hi:[1,0,1]
	v_pk_fma_f32 v[10:11], v[112:113], v[68:69], v[10:11]
	ds_read_b128 v[44:47], v26 offset:20992
	v_pk_fma_f32 v[10:11], v[114:115], v[70:71], v[10:11]
	ds_read_b128 v[48:51], v26 offset:21008
	v_add_f32_e32 v10, v10, v11
	ds_read_b32 v60, v27 offset:21504
	s_waitcnt lgkmcnt(9)
	v_pk_fma_f32 v[116:117], v[96:97], v[80:81], v[108:109] op_sel_hi:[0,1,1]
	v_add_f32_dpp v10, v10, v10 quad_perm:[1,0,3,2] row_mask:0xf bank_mask:0xf bound_ctrl:1
	v_pk_fma_f32 v[118:119], v[96:97], v[82:83], v[110:111] op_sel_hi:[0,1,1]
	v_pk_fma_f32 v[120:121], v[96:97], v[84:85], v[112:113] op_sel_hi:[0,1,1]
	v_add_f32_dpp v10, v10, v10 quad_perm:[2,3,0,1] row_mask:0xf bank_mask:0xf bound_ctrl:1
	v_pk_fma_f32 v[122:123], v[96:97], v[86:87], v[114:115] op_sel_hi:[0,1,1]
	v_pk_mul_f32 v[12:13], v[52:53], v[108:109]
	v_add_f32_dpp v10, v10, v10 row_half_mirror row_mask:0xf bank_mask:0xf bound_ctrl:1
	v_pk_fma_f32 v[12:13], v[54:55], v[110:111], v[12:13]
	ds_read_b128 v[36:39], v26 offset:20736
	v_pk_fma_f32 v[12:13], v[56:57], v[112:113], v[12:13]
	ds_read_b128 v[40:43], v26 offset:20752
	v_pk_fma_f32 v[12:13], v[58:59], v[114:115], v[12:13]
	ds_read_b128 v[52:55], v26 offset:21248
	v_add_f32_e32 v106, v12, v13
	ds_read_b128 v[56:59], v26 offset:21264
	ds_read_b128 v[64:67], v26 offset:21760
	v_add_f32_dpp v102, v106, v106 row_half_mirror row_mask:0xf bank_mask:0xa
	ds_read_b128 v[68:71], v26 offset:21776
	s_waitcnt lgkmcnt(9)
	v_pk_fma_f32 v[108:109], v[72:73], v[10:11], v[116:117] op_sel_hi:[1,0,1]
	v_pk_fma_f32 v[110:111], v[74:75], v[10:11], v[118:119] op_sel_hi:[1,0,1]
	v_pk_fma_f32 v[112:113], v[76:77], v[10:11], v[120:121] op_sel_hi:[1,0,1]
	v_pk_fma_f32 v[114:115], v[78:79], v[10:11], v[122:123] op_sel_hi:[1,0,1]
	v_pk_mul_f32 v[18:19], v[124:125], v[108:109]
	v_pk_mul_f32 v[20:21], v[126:127], v[110:111]
	v_pk_mul_f32 v[8:9], v[18:19], v[28:29]
	v_pk_mul_f32 v[22:23], v[128:129], v[112:113]
	v_pk_fma_f32 v[8:9], v[20:21], v[30:31], v[8:9]
	v_pk_mul_f32 v[24:25], v[130:131], v[114:115]
	v_pk_fma_f32 v[8:9], v[22:23], v[32:33], v[8:9]
	ds_read_b128 v[80:83], v26 offset:22272
	v_pk_fma_f32 v[8:9], v[24:25], v[34:35], v[8:9]
	ds_read_b128 v[84:87], v26 offset:22288
	v_add_f32_e32 v8, v8, v9
	ds_read_b32 v96, v27 offset:22784
	s_waitcnt lgkmcnt(9)
	v_pk_fma_f32 v[116:117], v[60:61], v[44:45], v[18:19] op_sel_hi:[0,1,1]
	v_add_f32_dpp v8, v8, v8 quad_perm:[1,0,3,2] row_mask:0xf bank_mask:0xf bound_ctrl:1
	v_pk_fma_f32 v[118:119], v[60:61], v[46:47], v[20:21] op_sel_hi:[0,1,1]
	v_pk_fma_f32 v[120:121], v[60:61], v[48:49], v[22:23] op_sel_hi:[0,1,1]
	v_add_f32_dpp v8, v8, v8 quad_perm:[2,3,0,1] row_mask:0xf bank_mask:0xf bound_ctrl:1
	v_pk_fma_f32 v[122:123], v[60:61], v[50:51], v[24:25] op_sel_hi:[0,1,1]
	v_pk_mul_f32 v[14:15], v[88:89], v[108:109]
	v_add_f32_dpp v8, v8, v8 row_half_mirror row_mask:0xf bank_mask:0xf bound_ctrl:1
	v_pk_fma_f32 v[14:15], v[90:91], v[110:111], v[14:15]
	ds_read_b128 v[72:75], v26 offset:22016
	v_pk_fma_f32 v[14:15], v[92:93], v[112:113], v[14:15]
	ds_read_b128 v[76:79], v26 offset:22032
	v_pk_fma_f32 v[14:15], v[94:95], v[114:115], v[14:15]
	ds_read_b128 v[88:91], v26 offset:22528
	v_add_f32_e32 v107, v14, v15
	ds_read_b128 v[92:95], v26 offset:22544
	v_add_f32_dpp v16, v100, v100 quad_perm:[2,3,0,1] row_mask:0xf bank_mask:0xf bound_ctrl:1
	v_add_f32_dpp v103, v107, v107 row_half_mirror row_mask:0xf bank_mask:0xa
	v_add_f32_dpp v62, v101, v101 quad_perm:[2,3,0,1] row_mask:0xf bank_mask:0xf bound_ctrl:1
	v_add_f32_dpp v17, v102, v102 quad_perm:[2,3,0,1] row_mask:0xf bank_mask:0xf bound_ctrl:1
	v_add_f32_dpp v63, v103, v103 quad_perm:[2,3,0,1] row_mask:0xf bank_mask:0xf bound_ctrl:1
	v_cndmask_b32_e64 v61, v16, v17, s[100:101]
	v_cndmask_b32_e64 v97, v62, v63, s[100:101]
	ds_read_b128 v[28:31], v26 offset:23040
	v_add_f32_dpp v16, v61, v61 quad_perm:[1,0,3,2] row_mask:0xf bank_mask:0xf bound_ctrl:1
	v_add_f32_dpp v17, v97, v97 quad_perm:[1,0,3,2] row_mask:0xf bank_mask:0xf bound_ctrl:1
	ds_read_b128 v[32:35], v26 offset:23056
	v_cndmask_b32_e64 v16, v16, v17, s[44:45]
	s_waitcnt lgkmcnt(6)
; #define LAS __attribute__((address_space(3)))
; __device__ __forceinline__ float sum8(float x) { x += dppf<0xB1>(x); x += dppf<0x4E>(x); x += dppf<0x141>(x); return x; }
; __global__ void __launch_bounds__(512, 2) fwd_megakernel(Params P) {
;     ...
;                             for (int tt = 0; tt < 32; tt += 8) {
;                                 float yk = 0.f;
;                                 const f32x4 ge0 = *(const LAS f32x4*)(pk + 40960 + (tt >> 3) * 256), ge1 = *(const LAS f32x4*)(pk + 40960 + (tt >> 3) * 256 + 16);
; #pragma unroll
;                                 for (int j = 0; j < 8; ++j) {
;                                     if (j < 7 || tt + 8 < 32) SCAN_LOAD(rg2[(j + 1) & 1], rv2[(j + 1) & 1], tt + j + 1);
;                                     __builtin_amdgcn_sched_barrier(0);
;                                     const f32x4 (&cur)[8] = rg2[j & 1]; const float curv = rv2[j & 1];
;                                     const f32x2 v2 = {curv, curv};
;                                     const f32x2 pa = v2 * cur[4].xy + Sa, pb = v2 * cur[4].zw + Sb, pc = v2 * cur[5].xy + Sc, pd = v2 * cur[5].zw + Sd;
;                                     f32x2 t0 = Sa * cur[0].xy; t0 = Sb * cur[0].zw + t0;
;                                     f32x2 t1 = Sc * cur[1].xy; t1 = Sd * cur[1].zw + t1;
;                                     const f32x2 t = t0 + t1;
;                                     float sa = sum8(t.x + t.y);
;                                     const f32x2 sa2 = {sa, sa};
;                                     Sa = sa2 * cur[2].xy + pa; Sb = sa2 * cur[2].zw + pb; Sc = sa2 * cur[3].xy + pc; Sd = sa2 * cur[3].zw + pd;
;                                     f32x2 u0 = Sa * cur[6].xy; u0 = Sb * cur[6].zw + u0;
;                                     f32x2 u1 = Sc * cur[7].xy; u1 = Sd * cur[7].zw + u1;
;                                     const f32x2 u = u0 + u1;
;                                     const float y = sum8(u.x + u.y);
;                                     yk = (kq == j) ? y : yk;
;                                 }
;                                 Sa *= ge0.xy; Sb *= ge0.zw; Sc *= ge1.xy; Sd *= ge1.zw;
;                                 yout[(size_t)(c * 32 + tt + kq) * 1024] = (f16)yk;
	v_pk_fma_f32 v[18:19], v[36:37], v[8:9], v[116:117] op_sel_hi:[1,0,1]
	v_cvt_f16_f32_e32 v17, v16
	v_pk_fma_f32 v[20:21], v[38:39], v[8:9], v[118:119] op_sel_hi:[1,0,1]
	global_store_short v[98:99], v17, off
	v_pk_mul_f32 v[10:11], v[18:19], v[64:65]
	v_add_co_u32_e32 v98, vcc, 0x4000, v98
	v_pk_fma_f32 v[22:23], v[40:41], v[8:9], v[120:121] op_sel_hi:[1,0,1]
	v_pk_fma_f32 v[10:11], v[20:21], v[66:67], v[10:11]
	v_addc_co_u32_e32 v99, vcc, 0, v99, vcc
	v_pk_fma_f32 v[24:25], v[42:43], v[8:9], v[122:123] op_sel_hi:[1,0,1]
	v_pk_fma_f32 v[10:11], v[22:23], v[68:69], v[10:11]
	ds_read_b128 v[44:47], v26 offset:23552
	v_pk_fma_f32 v[10:11], v[24:25], v[70:71], v[10:11]
	ds_read_b128 v[48:51], v26 offset:23568
	v_add_f32_e32 v10, v10, v11
	ds_read_b32 v60, v27 offset:24064
	v_pk_fma_f32 v[116:117], v[96:97], v[80:81], v[18:19] op_sel_hi:[0,1,1]
	v_add_f32_dpp v10, v10, v10 quad_perm:[1,0,3,2] row_mask:0xf bank_mask:0xf bound_ctrl:1
	v_pk_fma_f32 v[118:119], v[96:97], v[82:83], v[20:21] op_sel_hi:[0,1,1]
	v_pk_fma_f32 v[120:121], v[96:97], v[84:85], v[22:23] op_sel_hi:[0,1,1]
	v_add_f32_dpp v10, v10, v10 quad_perm:[2,3,0,1] row_mask:0xf bank_mask:0xf bound_ctrl:1
	v_pk_fma_f32 v[122:123], v[96:97], v[86:87], v[24:25] op_sel_hi:[0,1,1]
	v_pk_mul_f32 v[12:13], v[52:53], v[18:19]
	v_add_f32_dpp v10, v10, v10 row_half_mirror row_mask:0xf bank_mask:0xf bound_ctrl:1
	v_pk_fma_f32 v[12:13], v[54:55], v[20:21], v[12:13]
	ds_read_b128 v[36:39], v26 offset:23296
	v_pk_fma_f32 v[12:13], v[56:57], v[22:23], v[12:13]
	ds_read_b128 v[40:43], v26 offset:23312
	v_pk_fma_f32 v[12:13], v[58:59], v[24:25], v[12:13]
	ds_read_b128 v[52:55], v26 offset:23808
	v_add_f32_e32 v100, v12, v13
	ds_read_b128 v[56:59], v26 offset:23824
	ds_read_b128 v[124:127], v26 offset:41472
	ds_read_b128 v[128:131], v26 offset:41488
	ds_read_b128 v[64:67], v26 offset:24320
	ds_read_b128 v[68:71], v26 offset:24336
	s_waitcnt lgkmcnt(11)
	v_pk_fma_f32 v[18:19], v[72:73], v[10:11], v[116:117] op_sel_hi:[1,0,1]
	v_pk_fma_f32 v[20:21], v[74:75], v[10:11], v[118:119] op_sel_hi:[1,0,1]
	v_pk_mul_f32 v[8:9], v[18:19], v[28:29]
	v_pk_fma_f32 v[22:23], v[76:77], v[10:11], v[120:121] op_sel_hi:[1,0,1]
	v_pk_fma_f32 v[8:9], v[20:21], v[30:31], v[8:9]
	v_pk_fma_f32 v[24:25], v[78:79], v[10:11], v[122:123] op_sel_hi:[1,0,1]
	v_pk_fma_f32 v[8:9], v[22:23], v[32:33], v[8:9]
	ds_read_b128 v[80:83], v26 offset:24832
	v_pk_fma_f32 v[8:9], v[24:25], v[34:35], v[8:9]
	ds_read_b128 v[84:87], v26 offset:24848
	v_add_f32_e32 v8, v8, v9
	ds_read_b32 v96, v27 offset:25344
	s_waitcnt lgkmcnt(11)
	v_pk_fma_f32 v[116:117], v[60:61], v[44:45], v[18:19] op_sel_hi:[0,1,1]
	v_add_f32_dpp v8, v8, v8 quad_perm:[1,0,3,2] row_mask:0xf bank_mask:0xf bound_ctrl:1
	v_pk_fma_f32 v[118:119], v[60:61], v[46:47], v[20:21] op_sel_hi:[0,1,1]
	v_pk_fma_f32 v[120:121], v[60:61], v[48:49], v[22:23] op_sel_hi:[0,1,1]
	v_add_f32_dpp v8, v8, v8 quad_perm:[2,3,0,1] row_mask:0xf bank_mask:0xf bound_ctrl:1
	v_pk_fma_f32 v[122:123], v[60:61], v[50:51], v[24:25] op_sel_hi:[0,1,1]
	v_pk_mul_f32 v[14:15], v[88:89], v[18:19]
	v_add_f32_dpp v8, v8, v8 row_half_mirror row_mask:0xf bank_mask:0xf bound_ctrl:1
	v_pk_fma_f32 v[14:15], v[90:91], v[20:21], v[14:15]
	ds_read_b128 v[72:75], v26 offset:24576
	v_pk_fma_f32 v[14:15], v[92:93], v[22:23], v[14:15]
	ds_read_b128 v[76:79], v26 offset:24592
	v_pk_fma_f32 v[14:15], v[94:95], v[24:25], v[14:15]
	ds_read_b128 v[88:91], v26 offset:25088
	v_add_f32_e32 v101, v14, v15
	ds_read_b128 v[92:95], v26 offset:25104
	v_add_f32_dpp v100, v100, v100 row_half_mirror row_mask:0xf bank_mask:0x5
	ds_read_b128 v[28:31], v26 offset:25600
	ds_read_b128 v[32:35], v26 offset:25616
	s_waitcnt lgkmcnt(9)
	v_pk_fma_f32 v[18:19], v[36:37], v[8:9], v[116:117] op_sel_hi:[1,0,1]
	v_pk_fma_f32 v[20:21], v[38:39], v[8:9], v[118:119] op_sel_hi:[1,0,1]
	v_pk_mul_f32 v[10:11], v[18:19], v[64:65]
	v_pk_fma_f32 v[22:23], v[40:41], v[8:9], v[120:121] op_sel_hi:[1,0,1]
	v_pk_fma_f32 v[10:11], v[20:21], v[66:67], v[10:11]
	v_pk_fma_f32 v[24:25], v[42:43], v[8:9], v[122:123] op_sel_hi:[1,0,1]
	v_pk_fma_f32 v[10:11], v[22:23], v[68:69], v[10:11]
	ds_read_b128 v[44:47], v26 offset:26112
	v_pk_fma_f32 v[10:11], v[24:25], v[70:71], v[10:11]
	ds_read_b128 v[48:51], v26 offset:26128
	v_add_f32_e32 v10, v10, v11
	ds_read_b32 v60, v27 offset:26624
	s_waitcnt lgkmcnt(9)
	v_pk_fma_f32 v[116:117], v[96:97], v[80:81], v[18:19] op_sel_hi:[0,1,1]
	v_add_f32_dpp v10, v10, v10 quad_perm:[1,0,3,2] row_mask:0xf bank_mask:0xf bound_ctrl:1
	v_pk_fma_f32 v[118:119], v[96:97], v[82:83], v[20:21] op_sel_hi:[0,1,1]
	v_pk_fma_f32 v[120:121], v[96:97], v[84:85], v[22:23] op_sel_hi:[0,1,1]
	v_add_f32_dpp v10, v10, v10 quad_perm:[2,3,0,1] row_mask:0xf bank_mask:0xf bound_ctrl:1
	v_pk_fma_f32 v[122:123], v[96:97], v[86:87], v[24:25] op_sel_hi:[0,1,1]
	v_pk_mul_f32 v[12:13], v[52:53], v[18:19]
	v_add_f32_dpp v10, v10, v10 row_half_mirror row_mask:0xf bank_mask:0xf bound_ctrl:1
	v_pk_fma_f32 v[12:13], v[54:55], v[20:21], v[12:13]
	ds_read_b128 v[36:39], v26 offset:25856
	v_pk_fma_f32 v[12:13], v[56:57], v[22:23], v[12:13]
	ds_read_b128 v[40:43], v26 offset:25872
	v_pk_fma_f32 v[12:13], v[58:59], v[24:25], v[12:13]
	ds_read_b128 v[52:55], v26 offset:26368
	v_add_f32_e32 v102, v12, v13
	ds_read_b128 v[56:59], v26 offset:26384
	v_add_f32_dpp v101, v101, v101 row_half_mirror row_mask:0xf bank_mask:0x5
	ds_read_b128 v[64:67], v26 offset:26880
	ds_read_b128 v[68:71], v26 offset:26896
	s_waitcnt lgkmcnt(9)
; #define LAS __attribute__((address_space(3)))
; __device__ __forceinline__ float sum8(float x) { x += dppf<0xB1>(x); x += dppf<0x4E>(x); x += dppf<0x141>(x); return x; }
; __global__ void __launch_bounds__(512, 2) fwd_megakernel(Params P) {
;     ...
;                             for (int tt = 0; tt < 32; tt += 8) {
;                                 float yk = 0.f;
;                                 const f32x4 ge0 = *(const LAS f32x4*)(pk + 40960 + (tt >> 3) * 256), ge1 = *(const LAS f32x4*)(pk + 40960 + (tt >> 3) * 256 + 16);
; #pragma unroll
;                                 for (int j = 0; j < 8; ++j) {
;                                     if (j < 7 || tt + 8 < 32) SCAN_LOAD(rg2[(j + 1) & 1], rv2[(j + 1) & 1], tt + j + 1);
;                                     __builtin_amdgcn_sched_barrier(0);
;                                     const f32x4 (&cur)[8] = rg2[j & 1]; const float curv = rv2[j & 1];
;                                     const f32x2 v2 = {curv, curv};
;                                     const f32x2 pa = v2 * cur[4].xy + Sa, pb = v2 * cur[4].zw + Sb, pc = v2 * cur[5].xy + Sc, pd = v2 * cur[5].zw + Sd;
;                                     f32x2 t0 = Sa * cur[0].xy; t0 = Sb * cur[0].zw + t0;
;                                     f32x2 t1 = Sc * cur[1].xy; t1 = Sd * cur[1].zw + t1;
;                                     const f32x2 t = t0 + t1;
;                                     float sa = sum8(t.x + t.y);
;                                     const f32x2 sa2 = {sa, sa};
;                                     Sa = sa2 * cur[2].xy + pa; Sb = sa2 * cur[2].zw + pb; Sc = sa2 * cur[3].xy + pc; Sd = sa2 * cur[3].zw + pd;
;                                     f32x2 u0 = Sa * cur[6].xy; u0 = Sb * cur[6].zw + u0;
;                                     f32x2 u1 = Sc * cur[7].xy; u1 = Sd * cur[7].zw + u1;
;                                     const f32x2 u = u0 + u1;
;                                     const float y = sum8(u.x + u.y);
;                                     yk = (kq == j) ? y : yk;
;                                 }
;                                 Sa *= ge0.xy; Sb *= ge0.zw; Sc *= ge1.xy; Sd *= ge1.zw;
;                                 yout[(size_t)(c * 32 + tt + kq) * 1024] = (f16)yk;
	v_pk_fma_f32 v[18:19], v[72:73], v[10:11], v[116:117] op_sel_hi:[1,0,1]
	v_pk_fma_f32 v[20:21], v[74:75], v[10:11], v[118:119] op_sel_hi:[1,0,1]
	v_pk_mul_f32 v[8:9], v[18:19], v[28:29]
	v_pk_fma_f32 v[22:23], v[76:77], v[10:11], v[120:121] op_sel_hi:[1,0,1]
	v_pk_fma_f32 v[8:9], v[20:21], v[30:31], v[8:9]
	v_pk_fma_f32 v[24:25], v[78:79], v[10:11], v[122:123] op_sel_hi:[1,0,1]
	v_pk_fma_f32 v[8:9], v[22:23], v[32:33], v[8:9]
	ds_read_b128 v[80:83], v26 offset:27392
	v_pk_fma_f32 v[8:9], v[24:25], v[34:35], v[8:9]
	ds_read_b128 v[84:87], v26 offset:27408
	v_add_f32_e32 v8, v8, v9
	ds_read_b32 v96, v27 offset:27904
	s_waitcnt lgkmcnt(9)
	v_pk_fma_f32 v[116:117], v[60:61], v[44:45], v[18:19] op_sel_hi:[0,1,1]
	v_add_f32_dpp v8, v8, v8 quad_perm:[1,0,3,2] row_mask:0xf bank_mask:0xf bound_ctrl:1
	v_pk_fma_f32 v[118:119], v[60:61], v[46:47], v[20:21] op_sel_hi:[0,1,1]
	v_pk_fma_f32 v[120:121], v[60:61], v[48:49], v[22:23] op_sel_hi:[0,1,1]
	v_add_f32_dpp v8, v8, v8 quad_perm:[2,3,0,1] row_mask:0xf bank_mask:0xf bound_ctrl:1
	v_pk_fma_f32 v[122:123], v[60:61], v[50:51], v[24:25] op_sel_hi:[0,1,1]
	v_pk_mul_f32 v[14:15], v[88:89], v[18:19]
	v_add_f32_dpp v8, v8, v8 row_half_mirror row_mask:0xf bank_mask:0xf bound_ctrl:1
	v_pk_fma_f32 v[14:15], v[90:91], v[20:21], v[14:15]
	ds_read_b128 v[72:75], v26 offset:27136
	v_pk_fma_f32 v[14:15], v[92:93], v[22:23], v[14:15]
	ds_read_b128 v[76:79], v26 offset:27152
	v_pk_fma_f32 v[14:15], v[94:95], v[24:25], v[14:15]
	ds_read_b128 v[88:91], v26 offset:27648
	v_add_f32_e32 v103, v14, v15
	ds_read_b128 v[92:95], v26 offset:27664
	v_add_f32_dpp v102, v102, v102 row_half_mirror row_mask:0xf bank_mask:0x5
	ds_read_b128 v[28:31], v26 offset:28160
	ds_read_b128 v[32:35], v26 offset:28176
	s_waitcnt lgkmcnt(9)
	v_pk_fma_f32 v[18:19], v[36:37], v[8:9], v[116:117] op_sel_hi:[1,0,1]
	v_pk_fma_f32 v[20:21], v[38:39], v[8:9], v[118:119] op_sel_hi:[1,0,1]
	v_pk_mul_f32 v[10:11], v[18:19], v[64:65]
	v_pk_fma_f32 v[22:23], v[40:41], v[8:9], v[120:121] op_sel_hi:[1,0,1]
	v_pk_fma_f32 v[10:11], v[20:21], v[66:67], v[10:11]
	v_pk_fma_f32 v[24:25], v[42:43], v[8:9], v[122:123] op_sel_hi:[1,0,1]
	v_pk_fma_f32 v[10:11], v[22:23], v[68:69], v[10:11]
	ds_read_b128 v[44:47], v26 offset:28672
	v_pk_fma_f32 v[10:11], v[24:25], v[70:71], v[10:11]
	ds_read_b128 v[48:51], v26 offset:28688
	v_add_f32_e32 v10, v10, v11
	ds_read_b32 v60, v27 offset:29184
	s_waitcnt lgkmcnt(9)
	v_pk_fma_f32 v[116:117], v[96:97], v[80:81], v[18:19] op_sel_hi:[0,1,1]
	v_add_f32_dpp v10, v10, v10 quad_perm:[1,0,3,2] row_mask:0xf bank_mask:0xf bound_ctrl:1
	v_pk_fma_f32 v[118:119], v[96:97], v[82:83], v[20:21] op_sel_hi:[0,1,1]
	v_pk_fma_f32 v[120:121], v[96:97], v[84:85], v[22:23] op_sel_hi:[0,1,1]
	v_add_f32_dpp v10, v10, v10 quad_perm:[2,3,0,1] row_mask:0xf bank_mask:0xf bound_ctrl:1
	v_pk_fma_f32 v[122:123], v[96:97], v[86:87], v[24:25] op_sel_hi:[0,1,1]
	v_pk_mul_f32 v[12:13], v[52:53], v[18:19]
	v_add_f32_dpp v10, v10, v10 row_half_mirror row_mask:0xf bank_mask:0xf bound_ctrl:1
	v_pk_fma_f32 v[12:13], v[54:55], v[20:21], v[12:13]
	ds_read_b128 v[36:39], v26 offset:28416
	v_pk_fma_f32 v[12:13], v[56:57], v[22:23], v[12:13]
	ds_read_b128 v[40:43], v26 offset:28432
	v_pk_fma_f32 v[12:13], v[58:59], v[24:25], v[12:13]
	ds_read_b128 v[52:55], v26 offset:28928
	v_add_f32_e32 v104, v12, v13
	ds_read_b128 v[56:59], v26 offset:28944
	v_add_f32_dpp v103, v103, v103 row_half_mirror row_mask:0xf bank_mask:0x5
	v_add_f32_dpp v100, v104, v104 row_half_mirror row_mask:0xf bank_mask:0xa
	ds_read_b128 v[64:67], v26 offset:29440
	ds_read_b128 v[68:71], v26 offset:29456
	s_waitcnt lgkmcnt(9)
	v_pk_fma_f32 v[18:19], v[72:73], v[10:11], v[116:117] op_sel_hi:[1,0,1]
	v_pk_fma_f32 v[20:21], v[74:75], v[10:11], v[118:119] op_sel_hi:[1,0,1]
	v_pk_mul_f32 v[8:9], v[18:19], v[28:29]
	v_pk_fma_f32 v[22:23], v[76:77], v[10:11], v[120:121] op_sel_hi:[1,0,1]
	v_pk_fma_f32 v[8:9], v[20:21], v[30:31], v[8:9]
	v_pk_fma_f32 v[24:25], v[78:79], v[10:11], v[122:123] op_sel_hi:[1,0,1]
	v_pk_fma_f32 v[8:9], v[22:23], v[32:33], v[8:9]
	ds_read_b128 v[80:83], v26 offset:29952
	v_pk_fma_f32 v[8:9], v[24:25], v[34:35], v[8:9]
	ds_read_b128 v[84:87], v26 offset:29968
	v_add_f32_e32 v8, v8, v9
	ds_read_b32 v96, v27 offset:30464
	s_waitcnt lgkmcnt(9)
	v_pk_fma_f32 v[116:117], v[60:61], v[44:45], v[18:19] op_sel_hi:[0,1,1]
	v_add_f32_dpp v8, v8, v8 quad_perm:[1,0,3,2] row_mask:0xf bank_mask:0xf bound_ctrl:1
	v_pk_fma_f32 v[118:119], v[60:61], v[46:47], v[20:21] op_sel_hi:[0,1,1]
	v_pk_fma_f32 v[120:121], v[60:61], v[48:49], v[22:23] op_sel_hi:[0,1,1]
	v_add_f32_dpp v8, v8, v8 quad_perm:[2,3,0,1] row_mask:0xf bank_mask:0xf bound_ctrl:1
	v_pk_fma_f32 v[122:123], v[60:61], v[50:51], v[24:25] op_sel_hi:[0,1,1]
	v_pk_mul_f32 v[14:15], v[88:89], v[18:19]
	v_add_f32_dpp v8, v8, v8 row_half_mirror row_mask:0xf bank_mask:0xf bound_ctrl:1
	v_pk_fma_f32 v[14:15], v[90:91], v[20:21], v[14:15]
	ds_read_b128 v[72:75], v26 offset:29696
	v_pk_fma_f32 v[14:15], v[92:93], v[22:23], v[14:15]
	ds_read_b128 v[76:79], v26 offset:29712
	v_pk_fma_f32 v[14:15], v[94:95], v[24:25], v[14:15]
	ds_read_b128 v[88:91], v26 offset:30208
	v_add_f32_e32 v105, v14, v15
	ds_read_b128 v[92:95], v26 offset:30224
	ds_read_b128 v[28:31], v26 offset:30720
	v_add_f32_dpp v101, v105, v105 row_half_mirror row_mask:0xf bank_mask:0xa
	ds_read_b128 v[32:35], v26 offset:30736
	s_waitcnt lgkmcnt(9)
; #define LAS __attribute__((address_space(3)))
; __device__ __forceinline__ float sum8(float x) { x += dppf<0xB1>(x); x += dppf<0x4E>(x); x += dppf<0x141>(x); return x; }
; __global__ void __launch_bounds__(512, 2) fwd_megakernel(Params P) {
;     ...
;                             for (int tt = 0; tt < 32; tt += 8) {
;                                 float yk = 0.f;
;                                 const f32x4 ge0 = *(const LAS f32x4*)(pk + 40960 + (tt >> 3) * 256), ge1 = *(const LAS f32x4*)(pk + 40960 + (tt >> 3) * 256 + 16);
; #pragma unroll
;                                 for (int j = 0; j < 8; ++j) {
;                                     if (j < 7 || tt + 8 < 32) SCAN_LOAD(rg2[(j + 1) & 1], rv2[(j + 1) & 1], tt + j + 1);
;                                     __builtin_amdgcn_sched_barrier(0);
;                                     const f32x4 (&cur)[8] = rg2[j & 1]; const float curv = rv2[j & 1];
;                                     const f32x2 v2 = {curv, curv};
;                                     const f32x2 pa = v2 * cur[4].xy + Sa, pb = v2 * cur[4].zw + Sb, pc = v2 * cur[5].xy + Sc, pd = v2 * cur[5].zw + Sd;
;                                     f32x2 t0 = Sa * cur[0].xy; t0 = Sb * cur[0].zw + t0;
;                                     f32x2 t1 = Sc * cur[1].xy; t1 = Sd * cur[1].zw + t1;
;                                     const f32x2 t = t0 + t1;
;                                     float sa = sum8(t.x + t.y);
;                                     const f32x2 sa2 = {sa, sa};
;                                     Sa = sa2 * cur[2].xy + pa; Sb = sa2 * cur[2].zw + pb; Sc = sa2 * cur[3].xy + pc; Sd = sa2 * cur[3].zw + pd;
;                                     f32x2 u0 = Sa * cur[6].xy; u0 = Sb * cur[6].zw + u0;
;                                     f32x2 u1 = Sc * cur[7].xy; u1 = Sd * cur[7].zw + u1;
;                                     const f32x2 u = u0 + u1;
;                                     const float y = sum8(u.x + u.y);
;                                     yk = (kq == j) ? y : yk;
;                                 }
;                                 Sa *= ge0.xy; Sb *= ge0.zw; Sc *= ge1.xy; Sd *= ge1.zw;
;                                 yout[(size_t)(c * 32 + tt + kq) * 1024] = (f16)yk;
	v_pk_fma_f32 v[18:19], v[36:37], v[8:9], v[116:117] op_sel_hi:[1,0,1]
	v_pk_fma_f32 v[20:21], v[38:39], v[8:9], v[118:119] op_sel_hi:[1,0,1]
	v_pk_mul_f32 v[10:11], v[18:19], v[64:65]
	v_pk_fma_f32 v[22:23], v[40:41], v[8:9], v[120:121] op_sel_hi:[1,0,1]
	v_pk_fma_f32 v[10:11], v[20:21], v[66:67], v[10:11]
	v_pk_fma_f32 v[24:25], v[42:43], v[8:9], v[122:123] op_sel_hi:[1,0,1]
	v_pk_fma_f32 v[10:11], v[22:23], v[68:69], v[10:11]
	ds_read_b128 v[44:47], v26 offset:31232
	v_pk_fma_f32 v[10:11], v[24:25], v[70:71], v[10:11]
	ds_read_b128 v[48:51], v26 offset:31248
	v_add_f32_e32 v10, v10, v11
	ds_read_b32 v60, v27 offset:31744
	s_waitcnt lgkmcnt(9)
	v_pk_fma_f32 v[116:117], v[96:97], v[80:81], v[18:19] op_sel_hi:[0,1,1]
	v_add_f32_dpp v10, v10, v10 quad_perm:[1,0,3,2] row_mask:0xf bank_mask:0xf bound_ctrl:1
	v_pk_fma_f32 v[118:119], v[96:97], v[82:83], v[20:21] op_sel_hi:[0,1,1]
	v_pk_fma_f32 v[120:121], v[96:97], v[84:85], v[22:23] op_sel_hi:[0,1,1]
	v_add_f32_dpp v10, v10, v10 quad_perm:[2,3,0,1] row_mask:0xf bank_mask:0xf bound_ctrl:1
	v_pk_fma_f32 v[122:123], v[96:97], v[86:87], v[24:25] op_sel_hi:[0,1,1]
	v_pk_mul_f32 v[12:13], v[52:53], v[18:19]
	v_add_f32_dpp v10, v10, v10 row_half_mirror row_mask:0xf bank_mask:0xf bound_ctrl:1
	v_pk_fma_f32 v[12:13], v[54:55], v[20:21], v[12:13]
	ds_read_b128 v[36:39], v26 offset:30976
	v_pk_fma_f32 v[12:13], v[56:57], v[22:23], v[12:13]
	ds_read_b128 v[40:43], v26 offset:30992
	v_pk_fma_f32 v[12:13], v[58:59], v[24:25], v[12:13]
	ds_read_b128 v[52:55], v26 offset:31488
	v_add_f32_e32 v106, v12, v13
	ds_read_b128 v[56:59], v26 offset:31504
	ds_read_b128 v[64:67], v26 offset:32000
	v_add_f32_dpp v102, v106, v106 row_half_mirror row_mask:0xf bank_mask:0xa
	ds_read_b128 v[68:71], v26 offset:32016
	s_waitcnt lgkmcnt(9)
	v_pk_fma_f32 v[18:19], v[72:73], v[10:11], v[116:117] op_sel_hi:[1,0,1]
	v_pk_fma_f32 v[20:21], v[74:75], v[10:11], v[118:119] op_sel_hi:[1,0,1]
	v_pk_fma_f32 v[22:23], v[76:77], v[10:11], v[120:121] op_sel_hi:[1,0,1]
	v_pk_fma_f32 v[24:25], v[78:79], v[10:11], v[122:123] op_sel_hi:[1,0,1]
	v_pk_mul_f32 v[108:109], v[124:125], v[18:19]
	v_pk_mul_f32 v[110:111], v[126:127], v[20:21]
	v_pk_mul_f32 v[8:9], v[108:109], v[28:29]
	v_pk_mul_f32 v[112:113], v[128:129], v[22:23]
	v_pk_fma_f32 v[8:9], v[110:111], v[30:31], v[8:9]
	v_pk_mul_f32 v[114:115], v[130:131], v[24:25]
	v_pk_fma_f32 v[8:9], v[112:113], v[32:33], v[8:9]
	ds_read_b128 v[80:83], v26 offset:32512
	v_pk_fma_f32 v[8:9], v[114:115], v[34:35], v[8:9]
	ds_read_b128 v[84:87], v26 offset:32528
	v_add_f32_e32 v8, v8, v9
	ds_read_b32 v96, v27 offset:33024
	s_waitcnt lgkmcnt(9)
	v_pk_fma_f32 v[116:117], v[60:61], v[44:45], v[108:109] op_sel_hi:[0,1,1]
	v_add_f32_dpp v8, v8, v8 quad_perm:[1,0,3,2] row_mask:0xf bank_mask:0xf bound_ctrl:1
	v_pk_fma_f32 v[118:119], v[60:61], v[46:47], v[110:111] op_sel_hi:[0,1,1]
	v_pk_fma_f32 v[120:121], v[60:61], v[48:49], v[112:113] op_sel_hi:[0,1,1]
	v_add_f32_dpp v8, v8, v8 quad_perm:[2,3,0,1] row_mask:0xf bank_mask:0xf bound_ctrl:1
	v_pk_fma_f32 v[122:123], v[60:61], v[50:51], v[114:115] op_sel_hi:[0,1,1]
	v_pk_mul_f32 v[14:15], v[88:89], v[18:19]
	v_add_f32_dpp v8, v8, v8 row_half_mirror row_mask:0xf bank_mask:0xf bound_ctrl:1
	v_pk_fma_f32 v[14:15], v[90:91], v[20:21], v[14:15]
	ds_read_b128 v[72:75], v26 offset:32256
	v_pk_fma_f32 v[14:15], v[92:93], v[22:23], v[14:15]
	ds_read_b128 v[76:79], v26 offset:32272
	v_pk_fma_f32 v[14:15], v[94:95], v[24:25], v[14:15]
	ds_read_b128 v[88:91], v26 offset:32768
	v_add_f32_e32 v107, v14, v15
	ds_read_b128 v[92:95], v26 offset:32784
	v_add_f32_dpp v16, v100, v100 quad_perm:[2,3,0,1] row_mask:0xf bank_mask:0xf bound_ctrl:1
	v_add_f32_dpp v103, v107, v107 row_half_mirror row_mask:0xf bank_mask:0xa
	v_add_f32_dpp v62, v101, v101 quad_perm:[2,3,0,1] row_mask:0xf bank_mask:0xf bound_ctrl:1
	v_add_f32_dpp v17, v102, v102 quad_perm:[2,3,0,1] row_mask:0xf bank_mask:0xf bound_ctrl:1
	v_add_f32_dpp v63, v103, v103 quad_perm:[2,3,0,1] row_mask:0xf bank_mask:0xf bound_ctrl:1
	v_cndmask_b32_e64 v61, v16, v17, s[100:101]
	v_cndmask_b32_e64 v97, v62, v63, s[100:101]
	ds_read_b128 v[28:31], v26 offset:33280
	v_add_f32_dpp v16, v61, v61 quad_perm:[1,0,3,2] row_mask:0xf bank_mask:0xf bound_ctrl:1
	v_add_f32_dpp v17, v97, v97 quad_perm:[1,0,3,2] row_mask:0xf bank_mask:0xf bound_ctrl:1
	ds_read_b128 v[32:35], v26 offset:33296
	v_cndmask_b32_e64 v16, v16, v17, s[44:45]
	s_waitcnt lgkmcnt(6)
	v_pk_fma_f32 v[108:109], v[36:37], v[8:9], v[116:117] op_sel_hi:[1,0,1]
	v_cvt_f16_f32_e32 v17, v16
	v_pk_fma_f32 v[110:111], v[38:39], v[8:9], v[118:119] op_sel_hi:[1,0,1]
	global_store_short v[98:99], v17, off
	v_pk_mul_f32 v[10:11], v[108:109], v[64:65]
	v_add_co_u32_e32 v98, vcc, 0x4000, v98
	v_pk_fma_f32 v[112:113], v[40:41], v[8:9], v[120:121] op_sel_hi:[1,0,1]
	v_pk_fma_f32 v[10:11], v[110:111], v[66:67], v[10:11]
	v_addc_co_u32_e32 v99, vcc, 0, v99, vcc
	v_pk_fma_f32 v[114:115], v[42:43], v[8:9], v[122:123] op_sel_hi:[1,0,1]
	v_pk_fma_f32 v[10:11], v[112:113], v[68:69], v[10:11]
	ds_read_b128 v[44:47], v26 offset:33792
	v_pk_fma_f32 v[10:11], v[114:115], v[70:71], v[10:11]
	ds_read_b128 v[48:51], v26 offset:33808
	v_add_f32_e32 v10, v10, v11
	ds_read_b32 v60, v27 offset:34304
	v_pk_fma_f32 v[116:117], v[96:97], v[80:81], v[108:109] op_sel_hi:[0,1,1]
	v_add_f32_dpp v10, v10, v10 quad_perm:[1,0,3,2] row_mask:0xf bank_mask:0xf bound_ctrl:1
	v_pk_fma_f32 v[118:119], v[96:97], v[82:83], v[110:111] op_sel_hi:[0,1,1]
	v_pk_fma_f32 v[120:121], v[96:97], v[84:85], v[112:113] op_sel_hi:[0,1,1]
	v_add_f32_dpp v10, v10, v10 quad_perm:[2,3,0,1] row_mask:0xf bank_mask:0xf bound_ctrl:1
	v_pk_fma_f32 v[122:123], v[96:97], v[86:87], v[114:115] op_sel_hi:[0,1,1]
	v_pk_mul_f32 v[12:13], v[52:53], v[108:109]
	v_add_f32_dpp v10, v10, v10 row_half_mirror row_mask:0xf bank_mask:0xf bound_ctrl:1
	v_pk_fma_f32 v[12:13], v[54:55], v[110:111], v[12:13]
	ds_read_b128 v[36:39], v26 offset:33536
	v_pk_fma_f32 v[12:13], v[56:57], v[112:113], v[12:13]
	ds_read_b128 v[40:43], v26 offset:33552
	v_pk_fma_f32 v[12:13], v[58:59], v[114:115], v[12:13]
	ds_read_b128 v[52:55], v26 offset:34048
	v_add_f32_e32 v100, v12, v13
	ds_read_b128 v[56:59], v26 offset:34064
	ds_read_b128 v[124:127], v26 offset:41728
	ds_read_b128 v[128:131], v26 offset:41744
	ds_read_b128 v[64:67], v26 offset:34560
	ds_read_b128 v[68:71], v26 offset:34576
	s_waitcnt lgkmcnt(11)
; #define LAS __attribute__((address_space(3)))
; __device__ __forceinline__ float sum8(float x) { x += dppf<0xB1>(x); x += dppf<0x4E>(x); x += dppf<0x141>(x); return x; }
; __global__ void __launch_bounds__(512, 2) fwd_megakernel(Params P) {
;     ...
;                             for (int tt = 0; tt < 32; tt += 8) {
;                                 float yk = 0.f;
;                                 const f32x4 ge0 = *(const LAS f32x4*)(pk + 40960 + (tt >> 3) * 256), ge1 = *(const LAS f32x4*)(pk + 40960 + (tt >> 3) * 256 + 16);
; #pragma unroll
;                                 for (int j = 0; j < 8; ++j) {
;                                     if (j < 7 || tt + 8 < 32) SCAN_LOAD(rg2[(j + 1) & 1], rv2[(j + 1) & 1], tt + j + 1);
;                                     __builtin_amdgcn_sched_barrier(0);
;                                     const f32x4 (&cur)[8] = rg2[j & 1]; const float curv = rv2[j & 1];
;                                     const f32x2 v2 = {curv, curv};
;                                     const f32x2 pa = v2 * cur[4].xy + Sa, pb = v2 * cur[4].zw + Sb, pc = v2 * cur[5].xy + Sc, pd = v2 * cur[5].zw + Sd;
;                                     f32x2 t0 = Sa * cur[0].xy; t0 = Sb * cur[0].zw + t0;
;                                     f32x2 t1 = Sc * cur[1].xy; t1 = Sd * cur[1].zw + t1;
;                                     const f32x2 t = t0 + t1;
;                                     float sa = sum8(t.x + t.y);
;                                     const f32x2 sa2 = {sa, sa};
;                                     Sa = sa2 * cur[2].xy + pa; Sb = sa2 * cur[2].zw + pb; Sc = sa2 * cur[3].xy + pc; Sd = sa2 * cur[3].zw + pd;
;                                     f32x2 u0 = Sa * cur[6].xy; u0 = Sb * cur[6].zw + u0;
;                                     f32x2 u1 = Sc * cur[7].xy; u1 = Sd * cur[7].zw + u1;
;                                     const f32x2 u = u0 + u1;
;                                     const float y = sum8(u.x + u.y);
;                                     yk = (kq == j) ? y : yk;
;                                 }
;                                 Sa *= ge0.xy; Sb *= ge0.zw; Sc *= ge1.xy; Sd *= ge1.zw;
;                                 yout[(size_t)(c * 32 + tt + kq) * 1024] = (f16)yk;
	v_pk_fma_f32 v[108:109], v[72:73], v[10:11], v[116:117] op_sel_hi:[1,0,1]
	v_pk_fma_f32 v[110:111], v[74:75], v[10:11], v[118:119] op_sel_hi:[1,0,1]
	v_pk_mul_f32 v[8:9], v[108:109], v[28:29]
	v_pk_fma_f32 v[112:113], v[76:77], v[10:11], v[120:121] op_sel_hi:[1,0,1]
	v_pk_fma_f32 v[8:9], v[110:111], v[30:31], v[8:9]
	v_pk_fma_f32 v[114:115], v[78:79], v[10:11], v[122:123] op_sel_hi:[1,0,1]
	v_pk_fma_f32 v[8:9], v[112:113], v[32:33], v[8:9]
	ds_read_b128 v[80:83], v26 offset:35072
	v_pk_fma_f32 v[8:9], v[114:115], v[34:35], v[8:9]
	ds_read_b128 v[84:87], v26 offset:35088
	v_add_f32_e32 v8, v8, v9
	ds_read_b32 v96, v27 offset:35584
	s_waitcnt lgkmcnt(11)
	v_pk_fma_f32 v[116:117], v[60:61], v[44:45], v[108:109] op_sel_hi:[0,1,1]
	v_add_f32_dpp v8, v8, v8 quad_perm:[1,0,3,2] row_mask:0xf bank_mask:0xf bound_ctrl:1
	v_pk_fma_f32 v[118:119], v[60:61], v[46:47], v[110:111] op_sel_hi:[0,1,1]
	v_pk_fma_f32 v[120:121], v[60:61], v[48:49], v[112:113] op_sel_hi:[0,1,1]
	v_add_f32_dpp v8, v8, v8 quad_perm:[2,3,0,1] row_mask:0xf bank_mask:0xf bound_ctrl:1
	v_pk_fma_f32 v[122:123], v[60:61], v[50:51], v[114:115] op_sel_hi:[0,1,1]
	v_pk_mul_f32 v[14:15], v[88:89], v[108:109]
	v_add_f32_dpp v8, v8, v8 row_half_mirror row_mask:0xf bank_mask:0xf bound_ctrl:1
	v_pk_fma_f32 v[14:15], v[90:91], v[110:111], v[14:15]
	ds_read_b128 v[72:75], v26 offset:34816
	v_pk_fma_f32 v[14:15], v[92:93], v[112:113], v[14:15]
	ds_read_b128 v[76:79], v26 offset:34832
	v_pk_fma_f32 v[14:15], v[94:95], v[114:115], v[14:15]
	ds_read_b128 v[88:91], v26 offset:35328
	v_add_f32_e32 v101, v14, v15
	ds_read_b128 v[92:95], v26 offset:35344
	v_add_f32_dpp v100, v100, v100 row_half_mirror row_mask:0xf bank_mask:0x5
	ds_read_b128 v[28:31], v26 offset:35840
	ds_read_b128 v[32:35], v26 offset:35856
	s_waitcnt lgkmcnt(9)
	v_pk_fma_f32 v[108:109], v[36:37], v[8:9], v[116:117] op_sel_hi:[1,0,1]
	v_pk_fma_f32 v[110:111], v[38:39], v[8:9], v[118:119] op_sel_hi:[1,0,1]
	v_pk_mul_f32 v[10:11], v[108:109], v[64:65]
	v_pk_fma_f32 v[112:113], v[40:41], v[8:9], v[120:121] op_sel_hi:[1,0,1]
	v_pk_fma_f32 v[10:11], v[110:111], v[66:67], v[10:11]
	v_pk_fma_f32 v[114:115], v[42:43], v[8:9], v[122:123] op_sel_hi:[1,0,1]
	v_pk_fma_f32 v[10:11], v[112:113], v[68:69], v[10:11]
	ds_read_b128 v[44:47], v26 offset:36352
	v_pk_fma_f32 v[10:11], v[114:115], v[70:71], v[10:11]
	ds_read_b128 v[48:51], v26 offset:36368
	v_add_f32_e32 v10, v10, v11
	ds_read_b32 v60, v27 offset:36864
	s_waitcnt lgkmcnt(9)
	v_pk_fma_f32 v[116:117], v[96:97], v[80:81], v[108:109] op_sel_hi:[0,1,1]
	v_add_f32_dpp v10, v10, v10 quad_perm:[1,0,3,2] row_mask:0xf bank_mask:0xf bound_ctrl:1
	v_pk_fma_f32 v[118:119], v[96:97], v[82:83], v[110:111] op_sel_hi:[0,1,1]
	v_pk_fma_f32 v[120:121], v[96:97], v[84:85], v[112:113] op_sel_hi:[0,1,1]
	v_add_f32_dpp v10, v10, v10 quad_perm:[2,3,0,1] row_mask:0xf bank_mask:0xf bound_ctrl:1
	v_pk_fma_f32 v[122:123], v[96:97], v[86:87], v[114:115] op_sel_hi:[0,1,1]
	v_pk_mul_f32 v[12:13], v[52:53], v[108:109]
	v_add_f32_dpp v10, v10, v10 row_half_mirror row_mask:0xf bank_mask:0xf bound_ctrl:1
	v_pk_fma_f32 v[12:13], v[54:55], v[110:111], v[12:13]
	ds_read_b128 v[36:39], v26 offset:36096
	v_pk_fma_f32 v[12:13], v[56:57], v[112:113], v[12:13]
	ds_read_b128 v[40:43], v26 offset:36112
	v_pk_fma_f32 v[12:13], v[58:59], v[114:115], v[12:13]
	ds_read_b128 v[52:55], v26 offset:36608
	v_add_f32_e32 v102, v12, v13
	ds_read_b128 v[56:59], v26 offset:36624
	v_add_f32_dpp v101, v101, v101 row_half_mirror row_mask:0xf bank_mask:0x5
	ds_read_b128 v[64:67], v26 offset:37120
	ds_read_b128 v[68:71], v26 offset:37136
	s_waitcnt lgkmcnt(9)
	v_pk_fma_f32 v[108:109], v[72:73], v[10:11], v[116:117] op_sel_hi:[1,0,1]
	v_pk_fma_f32 v[110:111], v[74:75], v[10:11], v[118:119] op_sel_hi:[1,0,1]
	v_pk_mul_f32 v[8:9], v[108:109], v[28:29]
	v_pk_fma_f32 v[112:113], v[76:77], v[10:11], v[120:121] op_sel_hi:[1,0,1]
	v_pk_fma_f32 v[8:9], v[110:111], v[30:31], v[8:9]
	v_pk_fma_f32 v[114:115], v[78:79], v[10:11], v[122:123] op_sel_hi:[1,0,1]
	v_pk_fma_f32 v[8:9], v[112:113], v[32:33], v[8:9]
	ds_read_b128 v[80:83], v26 offset:37632
	v_pk_fma_f32 v[8:9], v[114:115], v[34:35], v[8:9]
	ds_read_b128 v[84:87], v26 offset:37648
	v_add_f32_e32 v8, v8, v9
	ds_read_b32 v96, v27 offset:38144
	s_waitcnt lgkmcnt(9)
	v_pk_fma_f32 v[116:117], v[60:61], v[44:45], v[108:109] op_sel_hi:[0,1,1]
	v_add_f32_dpp v8, v8, v8 quad_perm:[1,0,3,2] row_mask:0xf bank_mask:0xf bound_ctrl:1
	v_pk_fma_f32 v[118:119], v[60:61], v[46:47], v[110:111] op_sel_hi:[0,1,1]
	v_pk_fma_f32 v[120:121], v[60:61], v[48:49], v[112:113] op_sel_hi:[0,1,1]
	v_add_f32_dpp v8, v8, v8 quad_perm:[2,3,0,1] row_mask:0xf bank_mask:0xf bound_ctrl:1
	v_pk_fma_f32 v[122:123], v[60:61], v[50:51], v[114:115] op_sel_hi:[0,1,1]
	v_pk_mul_f32 v[14:15], v[88:89], v[108:109]
	v_add_f32_dpp v8, v8, v8 row_half_mirror row_mask:0xf bank_mask:0xf bound_ctrl:1
	v_pk_fma_f32 v[14:15], v[90:91], v[110:111], v[14:15]
	ds_read_b128 v[72:75], v26 offset:37376
	v_pk_fma_f32 v[14:15], v[92:93], v[112:113], v[14:15]
	ds_read_b128 v[76:79], v26 offset:37392
	v_pk_fma_f32 v[14:15], v[94:95], v[114:115], v[14:15]
	ds_read_b128 v[88:91], v26 offset:37888
	v_add_f32_e32 v103, v14, v15
	ds_read_b128 v[92:95], v26 offset:37904
	v_add_f32_dpp v102, v102, v102 row_half_mirror row_mask:0xf bank_mask:0x5
	ds_read_b128 v[28:31], v26 offset:38400
	ds_read_b128 v[32:35], v26 offset:38416
	s_waitcnt lgkmcnt(9)
; #define LAS __attribute__((address_space(3)))
; __device__ __forceinline__ float sum8(float x) { x += dppf<0xB1>(x); x += dppf<0x4E>(x); x += dppf<0x141>(x); return x; }
; __global__ void __launch_bounds__(512, 2) fwd_megakernel(Params P) {
;     ...
;                             for (int tt = 0; tt < 32; tt += 8) {
;                                 float yk = 0.f;
;                                 const f32x4 ge0 = *(const LAS f32x4*)(pk + 40960 + (tt >> 3) * 256), ge1 = *(const LAS f32x4*)(pk + 40960 + (tt >> 3) * 256 + 16);
; #pragma unroll
;                                 for (int j = 0; j < 8; ++j) {
;                                     if (j < 7 || tt + 8 < 32) SCAN_LOAD(rg2[(j + 1) & 1], rv2[(j + 1) & 1], tt + j + 1);
;                                     __builtin_amdgcn_sched_barrier(0);
;                                     const f32x4 (&cur)[8] = rg2[j & 1]; const float curv = rv2[j & 1];
;                                     const f32x2 v2 = {curv, curv};
;                                     const f32x2 pa = v2 * cur[4].xy + Sa, pb = v2 * cur[4].zw + Sb, pc = v2 * cur[5].xy + Sc, pd = v2 * cur[5].zw + Sd;
;                                     f32x2 t0 = Sa * cur[0].xy; t0 = Sb * cur[0].zw + t0;
;                                     f32x2 t1 = Sc * cur[1].xy; t1 = Sd * cur[1].zw + t1;
;                                     const f32x2 t = t0 + t1;
;                                     float sa = sum8(t.x + t.y);
;                                     const f32x2 sa2 = {sa, sa};
;                                     Sa = sa2 * cur[2].xy + pa; Sb = sa2 * cur[2].zw + pb; Sc = sa2 * cur[3].xy + pc; Sd = sa2 * cur[3].zw + pd;
;                                     f32x2 u0 = Sa * cur[6].xy; u0 = Sb * cur[6].zw + u0;
;                                     f32x2 u1 = Sc * cur[7].xy; u1 = Sd * cur[7].zw + u1;
;                                     const f32x2 u = u0 + u1;
;                                     const float y = sum8(u.x + u.y);
;                                     yk = (kq == j) ? y : yk;
;                                 }
;                                 Sa *= ge0.xy; Sb *= ge0.zw; Sc *= ge1.xy; Sd *= ge1.zw;
;                                 yout[(size_t)(c * 32 + tt + kq) * 1024] = (f16)yk;
;                             }
;                             __syncthreads();
	v_pk_fma_f32 v[108:109], v[36:37], v[8:9], v[116:117] op_sel_hi:[1,0,1]
	v_pk_fma_f32 v[110:111], v[38:39], v[8:9], v[118:119] op_sel_hi:[1,0,1]
	v_pk_mul_f32 v[10:11], v[108:109], v[64:65]
	v_pk_fma_f32 v[112:113], v[40:41], v[8:9], v[120:121] op_sel_hi:[1,0,1]
	v_pk_fma_f32 v[10:11], v[110:111], v[66:67], v[10:11]
	v_pk_fma_f32 v[114:115], v[42:43], v[8:9], v[122:123] op_sel_hi:[1,0,1]
	v_pk_fma_f32 v[10:11], v[112:113], v[68:69], v[10:11]
	ds_read_b128 v[44:47], v26 offset:38912
	v_pk_fma_f32 v[10:11], v[114:115], v[70:71], v[10:11]
	ds_read_b128 v[48:51], v26 offset:38928
	v_add_f32_e32 v10, v10, v11
	ds_read_b32 v60, v27 offset:39424
	s_waitcnt lgkmcnt(9)
	v_pk_fma_f32 v[116:117], v[96:97], v[80:81], v[108:109] op_sel_hi:[0,1,1]
	v_add_f32_dpp v10, v10, v10 quad_perm:[1,0,3,2] row_mask:0xf bank_mask:0xf bound_ctrl:1
	v_pk_fma_f32 v[118:119], v[96:97], v[82:83], v[110:111] op_sel_hi:[0,1,1]
	v_pk_fma_f32 v[120:121], v[96:97], v[84:85], v[112:113] op_sel_hi:[0,1,1]
	v_add_f32_dpp v10, v10, v10 quad_perm:[2,3,0,1] row_mask:0xf bank_mask:0xf bound_ctrl:1
	v_pk_fma_f32 v[122:123], v[96:97], v[86:87], v[114:115] op_sel_hi:[0,1,1]
	v_pk_mul_f32 v[12:13], v[52:53], v[108:109]
	v_add_f32_dpp v10, v10, v10 row_half_mirror row_mask:0xf bank_mask:0xf bound_ctrl:1
	v_pk_fma_f32 v[12:13], v[54:55], v[110:111], v[12:13]
	ds_read_b128 v[36:39], v26 offset:38656
	v_pk_fma_f32 v[12:13], v[56:57], v[112:113], v[12:13]
	ds_read_b128 v[40:43], v26 offset:38672
	v_pk_fma_f32 v[12:13], v[58:59], v[114:115], v[12:13]
	ds_read_b128 v[52:55], v26 offset:39168
	v_add_f32_e32 v104, v12, v13
	ds_read_b128 v[56:59], v26 offset:39184
	v_add_f32_dpp v103, v103, v103 row_half_mirror row_mask:0xf bank_mask:0x5
	v_add_f32_dpp v100, v104, v104 row_half_mirror row_mask:0xf bank_mask:0xa
	ds_read_b128 v[64:67], v26 offset:39680
	ds_read_b128 v[68:71], v26 offset:39696
	s_waitcnt lgkmcnt(9)
	v_pk_fma_f32 v[108:109], v[72:73], v[10:11], v[116:117] op_sel_hi:[1,0,1]
	v_pk_fma_f32 v[110:111], v[74:75], v[10:11], v[118:119] op_sel_hi:[1,0,1]
	v_pk_mul_f32 v[8:9], v[108:109], v[28:29]
	v_pk_fma_f32 v[112:113], v[76:77], v[10:11], v[120:121] op_sel_hi:[1,0,1]
	v_pk_fma_f32 v[8:9], v[110:111], v[30:31], v[8:9]
	v_pk_fma_f32 v[114:115], v[78:79], v[10:11], v[122:123] op_sel_hi:[1,0,1]
	v_pk_fma_f32 v[8:9], v[112:113], v[32:33], v[8:9]
	ds_read_b128 v[80:83], v26 offset:40192
	v_pk_fma_f32 v[8:9], v[114:115], v[34:35], v[8:9]
	ds_read_b128 v[84:87], v26 offset:40208
	v_add_f32_e32 v8, v8, v9
	ds_read_b32 v96, v27 offset:40704
	s_waitcnt lgkmcnt(9)
	v_pk_fma_f32 v[116:117], v[60:61], v[44:45], v[108:109] op_sel_hi:[0,1,1]
	v_add_f32_dpp v8, v8, v8 quad_perm:[1,0,3,2] row_mask:0xf bank_mask:0xf bound_ctrl:1
	v_pk_fma_f32 v[118:119], v[60:61], v[46:47], v[110:111] op_sel_hi:[0,1,1]
	v_pk_fma_f32 v[120:121], v[60:61], v[48:49], v[112:113] op_sel_hi:[0,1,1]
	v_add_f32_dpp v8, v8, v8 quad_perm:[2,3,0,1] row_mask:0xf bank_mask:0xf bound_ctrl:1
	v_pk_fma_f32 v[122:123], v[60:61], v[50:51], v[114:115] op_sel_hi:[0,1,1]
	v_pk_mul_f32 v[14:15], v[88:89], v[108:109]
	v_add_f32_dpp v8, v8, v8 row_half_mirror row_mask:0xf bank_mask:0xf bound_ctrl:1
	v_pk_fma_f32 v[14:15], v[90:91], v[110:111], v[14:15]
	ds_read_b128 v[72:75], v26 offset:39936
	v_pk_fma_f32 v[14:15], v[92:93], v[112:113], v[14:15]
	ds_read_b128 v[76:79], v26 offset:39952
	v_pk_fma_f32 v[14:15], v[94:95], v[114:115], v[14:15]
	ds_read_b128 v[88:91], v26 offset:40448
	v_add_f32_e32 v105, v14, v15
	ds_read_b128 v[92:95], v26 offset:40464
	s_waitcnt lgkmcnt(7)
	v_pk_fma_f32 v[108:109], v[36:37], v[8:9], v[116:117] op_sel_hi:[1,0,1]
	v_add_f32_dpp v101, v105, v105 row_half_mirror row_mask:0xf bank_mask:0xa
	v_pk_fma_f32 v[110:111], v[38:39], v[8:9], v[118:119] op_sel_hi:[1,0,1]
	v_pk_mul_f32 v[10:11], v[108:109], v[64:65]
	v_pk_fma_f32 v[112:113], v[40:41], v[8:9], v[120:121] op_sel_hi:[1,0,1]
	v_pk_fma_f32 v[10:11], v[110:111], v[66:67], v[10:11]
	v_pk_fma_f32 v[114:115], v[42:43], v[8:9], v[122:123] op_sel_hi:[1,0,1]
	v_pk_fma_f32 v[10:11], v[112:113], v[68:69], v[10:11]
	s_waitcnt lgkmcnt(4)
	v_pk_fma_f32 v[116:117], v[96:97], v[80:81], v[108:109] op_sel_hi:[0,1,1]
	v_pk_fma_f32 v[10:11], v[114:115], v[70:71], v[10:11]
	v_pk_fma_f32 v[118:119], v[96:97], v[82:83], v[110:111] op_sel_hi:[0,1,1]
	v_add_f32_e32 v10, v10, v11
	v_pk_fma_f32 v[120:121], v[96:97], v[84:85], v[112:113] op_sel_hi:[0,1,1]
	v_pk_fma_f32 v[122:123], v[96:97], v[86:87], v[114:115] op_sel_hi:[0,1,1]
	v_add_f32_dpp v10, v10, v10 quad_perm:[1,0,3,2] row_mask:0xf bank_mask:0xf bound_ctrl:1
	v_pk_mul_f32 v[12:13], v[52:53], v[108:109]
	v_add_f32_dpp v16, v100, v100 quad_perm:[2,3,0,1] row_mask:0xf bank_mask:0xf bound_ctrl:1
	v_add_f32_dpp v10, v10, v10 quad_perm:[2,3,0,1] row_mask:0xf bank_mask:0xf bound_ctrl:1
	v_pk_fma_f32 v[12:13], v[54:55], v[110:111], v[12:13]
	v_add_f32_dpp v62, v101, v101 quad_perm:[2,3,0,1] row_mask:0xf bank_mask:0xf bound_ctrl:1
	v_add_f32_dpp v10, v10, v10 row_half_mirror row_mask:0xf bank_mask:0xf bound_ctrl:1
	v_pk_fma_f32 v[12:13], v[56:57], v[112:113], v[12:13]
	s_waitcnt lgkmcnt(2)
	v_pk_fma_f32 v[108:109], v[72:73], v[10:11], v[116:117] op_sel_hi:[1,0,1]
	v_pk_fma_f32 v[12:13], v[58:59], v[114:115], v[12:13]
	v_pk_fma_f32 v[110:111], v[74:75], v[10:11], v[118:119] op_sel_hi:[1,0,1]
	v_add_f32_e32 v106, v12, v13
	v_pk_fma_f32 v[112:113], v[76:77], v[10:11], v[120:121] op_sel_hi:[1,0,1]
	v_pk_fma_f32 v[114:115], v[78:79], v[10:11], v[122:123] op_sel_hi:[1,0,1]
	v_add_f32_dpp v102, v106, v106 row_half_mirror row_mask:0xf bank_mask:0xa
	v_pk_mul_f32 v[18:19], v[124:125], v[108:109]
	v_pk_mul_f32 v[20:21], v[126:127], v[110:111]
	v_pk_mul_f32 v[22:23], v[128:129], v[112:113]
	v_pk_mul_f32 v[24:25], v[130:131], v[114:115]
	s_waitcnt lgkmcnt(0)
	v_pk_mul_f32 v[14:15], v[88:89], v[108:109]
	v_add_f32_dpp v17, v102, v102 quad_perm:[2,3,0,1] row_mask:0xf bank_mask:0xf bound_ctrl:1
	v_pk_fma_f32 v[14:15], v[90:91], v[110:111], v[14:15]
	v_cndmask_b32_e64 v61, v16, v17, s[100:101]
	v_pk_fma_f32 v[14:15], v[92:93], v[112:113], v[14:15]
	s_nop 0
	v_pk_fma_f32 v[14:15], v[94:95], v[114:115], v[14:15]
	v_add_f32_dpp v16, v61, v61 quad_perm:[1,0,3,2] row_mask:0xf bank_mask:0xf bound_ctrl:1
	v_add_f32_e32 v107, v14, v15
	s_nop 1
	v_add_f32_dpp v103, v107, v107 row_half_mirror row_mask:0xf bank_mask:0xa
	s_nop 1
	v_add_f32_dpp v63, v103, v103 quad_perm:[2,3,0,1] row_mask:0xf bank_mask:0xf bound_ctrl:1
	s_nop 0
	v_cndmask_b32_e64 v97, v62, v63, s[100:101]
	s_nop 1
	v_add_f32_dpp v17, v97, v97 quad_perm:[1,0,3,2] row_mask:0xf bank_mask:0xf bound_ctrl:1
	s_nop 0
	v_cndmask_b32_e64 v16, v16, v17, s[44:45]
	s_nop 0
	v_cvt_f16_f32_e32 v17, v16
	s_nop 0
	global_store_short v[98:99], v17, off
	s_nop 0
	v_add_co_u32_e32 v98, vcc, 0x4000, v98
	s_nop 1
	v_addc_co_u32_e32 v99, vcc, 0, v99, vcc
	v_xor_b32_e32 v26, 0xa400, v26
	v_xor_b32_e32 v27, 0xa400, v27
	s_add_u32 s94, s94, 0x10000
	s_cmp_eq_u32 s94, 0x800000
	s_barrier
	s_cbranch_scc0 .Lscan_chunk
	s_setprio 0
	s_mov_b64 s[62:63], 0

; __global__ void __launch_bounds__(512, 2) fwd_megakernel(Params P) {
;     ...
;                         const size_t gbase = (m0 + tl) * 1024 + c0;
;                         const unsigned loff = (unsigned)(tl * 1280 + seg * 32);
;                         constexpr int NC = T / 32;
;                         f16x8 q[9];
; #pragma unroll
;                         for (int i = 0; i < 9; ++i) q[i] = (f16x8)(0);
;     ...
;                         FS_LOAD(0);
; #pragma unroll 1
;                         for (int c = 0; c <= NC; ++c) {
;     ...
;                                 if (c + 1 < NC) FS_LOAD(c + 1);
;                             }
;                             __syncthreads();
.LBB0_262:
	s_lshl_b32 s46, s40, 2
	v_lshlrev_b32_e32 v1, 1, v182
	s_cmp_eq_u32 s39, 0
	v_lshl_or_b32 v1, s44, 7, v1
	s_cselect_b64 s[94:95], -1, 0
	s_lshl_b64 s[44:45], s[92:93], 23
	v_or_b32_e32 v2, s44, v1
	v_mov_b32_e32 v3, s45
	s_lshl_b64 s[44:45], s[92:93], 18
	s_or_b32 s44, s44, s46
	s_mov_b32 s40, 0
	v_lshl_add_u64 v[2:3], v[136:137], 0, v[2:3]
	v_lshl_add_u64 v[140:141], v[138:139], 0, s[44:45]
	s_mov_b64 s[92:93], 0
	s_branch .LBB0_265
.LBB0_264:
	s_add_i32 s40, s40, 1
	s_add_u32 s92, s92, 0x10000
	s_addc_u32 s93, s93, 0
	s_cmp_eq_u32 s92, 0x810000
	v_lshl_add_u64 v[140:141], v[140:141], 0, s[84:85]
	s_waitcnt lgkmcnt(0)
	s_barrier
	s_cbranch_scc1 .LBB0_248

; __device__ __forceinline__ float sigm(float x) { return __builtin_amdgcn_rcpf(1.0f + __expf(-x)); }
; __global__ void __launch_bounds__(512, 2) fwd_megakernel(Params P) {
;     ...
;                                 float rr[8], rp[8], kr[8], kq8[8], lw[8], la[8], vv[8];
;                                 cv8(q[0], rr); cv8(q[1], rp); cv8(q[2], kr); cv8(q[3], kq8); cv8(q[4], lw); cv8(q[5], la);
;                                 if (L == 0) { float vr[8], vp[8]; cv8(q[6], vr); cv8(q[7], vp);
; #pragma unroll
;                                     for (int i = 0; i < 8; ++i) vv[i] = vr[i] + (vp[i] - vr[i]) * muv[i]; }
;                                 else { float lv[8], vf[8]; cv8(q[6], vv); cv8(q[7], lv); cv8(q[8], vf);
; #pragma unroll
;                                     for (int i = 0; i < 8; ++i) { const float nu = sigm(v0v[i] + lv[i]); vv[i] = vv[i] + (vf[i] - vv[i]) * nu; } }
;                                 float ro[8], ko[8], ewv[8], bo[8], nk[8]; float ss = 0.f, bsum = 0.f;
; #pragma unroll
;                                 for (int i = 0; i < 8; ++i) {
;                                     const float r = rr[i] + (rp[i] - rr[i]) * mur[i], k = kr[i] + (kq8[i] - kr[i]) * muk[i];
;                                     const float ew = sigm(w0v[i] + lw[i]) * 0.6065306597126334f;
;                                     ewv[i] = ew;
;                                     const float a = sigm(a0v[i] + la[i]);
;                                     const float kkv = k * kkp[i]; ss += kkv * kkv; nk[i] = kkv; bo[i] = a;
;                                     const float k2 = k * (1.0f + (a - 1.0f) * kap[i]);
;                                     ro[i] = r; ko[i] = k2; bsum += r * k2 * rkp[i];
.LBB0_270:
	v_cvt_f32_f16_sdwa v123, v111 dst_sel:DWORD dst_unused:UNUSED_PAD src0_sel:WORD_1
	v_cvt_f32_f16_e32 v151, v88
	v_cvt_f32_f16_sdwa v167, v86 dst_sel:DWORD dst_unused:UNUSED_PAD src0_sel:WORD_1
	v_cvt_f32_f16_e32 v166, v86
	v_sub_f32_e32 v1, v1, v123
	v_cvt_f32_f16_sdwa v169, v106 dst_sel:DWORD dst_unused:UNUSED_PAD src0_sel:WORD_1
	v_cvt_f32_f16_e32 v168, v106
	v_fma_mix_f32 v123, v1, v150, v111 op_sel:[0,0,1] op_sel_hi:[0,0,1]
	v_add_f32_e32 v1, v36, v151
	v_cvt_f32_f16_sdwa v127, v80 dst_sel:DWORD dst_unused:UNUSED_PAD src0_sel:WORD_1
	v_cvt_f32_f16_e32 v126, v80
	v_cvt_f32_f16_sdwa v131, v82 dst_sel:DWORD dst_unused:UNUSED_PAD src0_sel:WORD_1
	v_cvt_f32_f16_e32 v130, v82
	v_cvt_f32_f16_sdwa v145, v96 dst_sel:DWORD dst_unused:UNUSED_PAD src0_sel:WORD_1
	v_cvt_f32_f16_e32 v144, v96
	v_cvt_f32_f16_sdwa v159, v98 dst_sel:DWORD dst_unused:UNUSED_PAD src0_sel:WORD_1
	v_cvt_f32_f16_e32 v158, v98
	v_cvt_f32_f16_sdwa v162, v88 dst_sel:DWORD dst_unused:UNUSED_PAD src0_sel:WORD_1
	v_cvt_f32_f16_e32 v163, v89
	v_cvt_f32_f16_sdwa v170, v89 dst_sel:DWORD dst_unused:UNUSED_PAD src0_sel:WORD_1
	v_cvt_f32_f16_e32 v171, v90
	v_cvt_f32_f16_sdwa v172, v90 dst_sel:DWORD dst_unused:UNUSED_PAD src0_sel:WORD_1
	v_cvt_f32_f16_e32 v176, v91
	v_cvt_f32_f16_sdwa v177, v91 dst_sel:DWORD dst_unused:UNUSED_PAD src0_sel:WORD_1
	v_mul_f32_e32 v1, 0xbfb8aa3b, v1
	v_exp_f32_e32 v1, v1
	v_cvt_f32_f16_sdwa v125, v87 dst_sel:DWORD dst_unused:UNUSED_PAD src0_sel:WORD_1
	v_cvt_f32_f16_e32 v124, v87
	v_cvt_f32_f16_sdwa v175, v107 dst_sel:DWORD dst_unused:UNUSED_PAD src0_sel:WORD_1
	v_cvt_f32_f16_e32 v174, v107
	v_pk_add_f32 v[168:169], v[168:169], v[166:167] neg_lo:[0,1] neg_hi:[0,1]
	v_pk_add_f32 v[152:153], v[144:145], v[126:127] neg_lo:[0,1] neg_hi:[0,1]
	v_add_f32_e32 v145, v37, v162
	v_add_f32_e32 v150, v38, v163
	v_add_f32_e32 v151, v39, v170
	v_pk_add_f32 v[162:163], v[158:159], v[130:131] neg_lo:[0,1] neg_hi:[0,1]
	v_add_f32_e32 v158, v32, v171
	v_add_f32_e32 v159, v33, v172
	v_pk_fma_f32 v[168:169], v[168:169], v[24:25], v[166:167]
	v_add_f32_e32 v166, v34, v176
	v_add_f32_e32 v167, v35, v177
	v_add_f32_e32 v1, 1.0, v1
	v_mul_f32_e32 v151, 0xbfb8aa3b, v151
	v_mul_f32_e32 v158, 0xbfb8aa3b, v158
	v_mul_f32_e32 v159, 0xbfb8aa3b, v159
	v_mul_f32_e32 v166, 0xbfb8aa3b, v166
	v_mul_f32_e32 v167, 0xbfb8aa3b, v167
	v_rcp_f32_e32 v1, v1
	v_mul_f32_e32 v145, 0xbfb8aa3b, v145
	v_exp_f32_e32 v151, v151
	v_exp_f32_e32 v158, v158
	v_exp_f32_e32 v159, v159
	v_pk_add_f32 v[174:175], v[174:175], v[124:125] neg_lo:[0,1] neg_hi:[0,1]
	v_exp_f32_e32 v166, v166
	v_exp_f32_e32 v167, v167
	v_cvt_f32_f16_sdwa v197, v93 dst_sel:DWORD dst_unused:UNUSED_PAD src0_sel:WORD_1
	v_cvt_f32_f16_e32 v199, v94
	v_cvt_f32_f16_sdwa v200, v94 dst_sel:DWORD dst_unused:UNUSED_PAD src0_sel:WORD_1
	v_cvt_f32_f16_e32 v201, v95
	v_cvt_f32_f16_sdwa v202, v95 dst_sel:DWORD dst_unused:UNUSED_PAD src0_sel:WORD_1
	v_mov_b32_e32 v238, v81
	v_mov_b32_e32 v239, v83
	v_mov_b32_e32 v240, v84
	v_mov_b32_e32 v241, v85
	v_mov_b32_e32 v242, v92
	v_mov_b32_e32 v243, v93
	v_mov_b32_e32 v244, v97
	v_mov_b32_e32 v245, v99
	v_mov_b32_e32 v246, v104
	v_mov_b32_e32 v247, v105
	s_cmpk_gt_u32 s40, 0x7e
	s_cbranch_scc1 .Lstg_noload
	v_subrev_u32_e32 v248, s42, v2
	v_add_u32_e32 v248, 0xb010000, v248
	v_add_u32_e32 v248, s92, v248
	s_cmp_lg_u64 s[48:49], 0
	global_load_dwordx4 v[80:83], v248, s[42:43]
	global_load_dwordx4 v[84:87], v248, s[56:57]
	global_load_dwordx4 v[88:91], v248, s[66:67]
	global_load_dwordx4 v[92:95], v248, s[68:69]
	global_load_dwordx4 v[96:99], v248, s[42:43] offset:-2048
	global_load_dwordx4 v[104:107], v248, s[56:57] offset:-2048
	s_cbranch_scc0 .Lstg_l0
	global_load_dwordx4 v[108:111], v248, s[72:73]
	global_load_dwordx4 v[112:115], v248, s[74:75]
	global_load_dwordx4 v[100:103], v248, s[82:83]
	s_branch .Lstg_noload
.Lstg_l0:
	global_load_dwordx4 v[108:111], v248, s[60:61]
	global_load_dwordx4 v[112:115], v248, s[60:61] offset:-2048
.Lstg_noload:
	v_exp_f32_e32 v145, v145
	v_pk_fma_f32 v[174:175], v[174:175], v[26:27], v[124:125]
	v_and_b32_e32 v124, 64, v236
	v_add_u32_e32 v125, -8, v236
	v_cmp_lt_i32_e32 vcc, v125, v124
	v_mul_f32_e32 v203, 0x3f1b4598, v1
	v_add_f32_e32 v151, 1.0, v151
	v_cndmask_b32_e32 v125, v125, v236, vcc
	v_add_f32_e32 v158, 1.0, v158
	v_add_f32_e32 v159, 1.0, v159
	v_add_f32_e32 v166, 1.0, v166
	v_add_f32_e32 v167, 1.0, v167
	v_lshlrev_b32_e32 v125, 2, v125
	v_add_f32_e32 v145, 1.0, v145
	v_rcp_f32_e32 v198, v151
	v_add_f32_e32 v151, v47, v197
	v_rcp_f32_e32 v197, v158
	v_add_f32_e32 v158, v40, v199
	v_rcp_f32_e32 v199, v159
	v_add_f32_e32 v159, v41, v200
	v_rcp_f32_e32 v200, v166
	v_add_f32_e32 v166, v42, v201
	v_rcp_f32_e32 v201, v167
	v_add_f32_e32 v167, v43, v202
	ds_bpermute_b32 v202, v125, v203
	v_rcp_f32_e32 v195, v145
	v_mul_f32_e32 v150, 0xbfb8aa3b, v150
	v_exp_f32_e32 v150, v150
	v_mul_f32_e32 v206, 0x3f1b4598, v198
	v_mul_f32_e32 v204, 0x3f1b4598, v195
	s_waitcnt lgkmcnt(0)
	v_fmac_f32_e32 v202, 0x3f1b4598, v1
	v_add_f32_e32 v150, 1.0, v150
	v_cndmask_b32_e64 v202, v202, v203, s[28:29]
	ds_bpermute_b32 v203, v125, v204
	v_rcp_f32_e32 v196, v150
	v_mul_f32_e32 v207, 0x3f1b4598, v197
	v_mul_f32_e32 v208, 0x3f1b4598, v199
	v_mul_f32_e32 v209, 0x3f1b4598, v200
	v_mul_f32_e32 v205, 0x3f1b4598, v196
	s_waitcnt lgkmcnt(0)
	v_fmac_f32_e32 v203, 0x3f1b4598, v195
	v_cndmask_b32_e64 v203, v203, v204, s[28:29]
	ds_bpermute_b32 v204, v125, v205
	v_mul_f32_e32 v210, 0x3f1b4598, v201
	v_cvt_f32_f16_e32 v173, v242
	v_cvt_f32_f16_sdwa v178, v242 dst_sel:DWORD dst_unused:UNUSED_PAD src0_sel:WORD_1
	v_cvt_f32_f16_sdwa v149, v240 dst_sel:DWORD dst_unused:UNUSED_PAD src0_sel:WORD_1
	s_waitcnt lgkmcnt(0)
; __device__ __forceinline__ float sigm(float x) { return __builtin_amdgcn_rcpf(1.0f + __expf(-x)); }
; __device__ __forceinline__ float sum8(float x) { x += dppf<0xB1>(x); x += dppf<0x4E>(x); x += dppf<0x141>(x); return x; }
; __global__ void __launch_bounds__(512, 2) fwd_megakernel(Params P) {
;     ...
;                                     const float r = rr[i] + (rp[i] - rr[i]) * mur[i], k = kr[i] + (kq8[i] - kr[i]) * muk[i];
;                                     const float ew = sigm(w0v[i] + lw[i]) * 0.6065306597126334f;
;                                     ewv[i] = ew;
;                                     const float a = sigm(a0v[i] + la[i]);
;                                     const float kkv = k * kkp[i]; ss += kkv * kkv; nk[i] = kkv; bo[i] = a;
;                                     const float k2 = k * (1.0f + (a - 1.0f) * kap[i]);
;                                     ro[i] = r; ko[i] = k2; bsum += r * k2 * rkp[i];
;                                 }
;                                 ss = sum8(ss); bsum = sum8(bsum);
;                                 const float inv = __builtin_amdgcn_rsqf(fmaxf(ss, 1e-24f));
; #pragma unroll
;                                 for (int i = 0; i < 8; ++i) { const float kk = nk[i] * inv; nk[i] = -kk; bo[i] = kk * bo[i]; }
;                                 float G[8];
; #pragma unroll
;                                 for (int i = 0; i < 8; ++i) G[i] = ewv[i];
; #pragma unroll
;                                 for (int d = 8; d < 64; d <<= 1) {
; #pragma unroll
;                                     for (int i = 0; i < 8; ++i) { const float up = __shfl_up(G[i], d); if (lane >= d) G[i] += up; } }
;                                 float ecur[8];
; #pragma unroll
;                                 for (int i = 0; i < 8; ++i) { const float ec = __expf(-G[i]), ei = __expf(G[i]), ep = __expf(ewv[i] - G[i]);
;                                     ecur[i] = ec; nk[i] *= ep; ro[i] *= ec; bo[i] *= ei; ko[i] *= ei; }
	v_fmac_f32_e32 v204, 0x3f1b4598, v196
	v_cndmask_b32_e64 v204, v204, v205, s[28:29]
	ds_bpermute_b32 v205, v125, v206
	v_add_f32_e32 v144, v44, v173
	v_add_f32_e32 v145, v45, v178
	v_mul_f32_e32 v144, 0xbfb8aa3b, v144
	v_mul_f32_e32 v145, 0xbfb8aa3b, v145
	s_waitcnt lgkmcnt(0)
	v_fmac_f32_e32 v205, 0x3f1b4598, v198
	v_cndmask_b32_e64 v205, v205, v206, s[28:29]
	ds_bpermute_b32 v206, v125, v207
	v_exp_f32_e32 v144, v144
	v_exp_f32_e32 v145, v145
	v_cvt_f32_f16_e32 v148, v240
	v_cvt_f32_f16_sdwa v155, v246 dst_sel:DWORD dst_unused:UNUSED_PAD src0_sel:WORD_1
	s_waitcnt lgkmcnt(0)
	v_fmac_f32_e32 v206, 0x3f1b4598, v197
	v_cndmask_b32_e64 v206, v206, v207, s[28:29]
	ds_bpermute_b32 v207, v125, v208
	v_add_f32_e32 v144, 1.0, v144
	v_add_f32_e32 v145, 1.0, v145
	v_cvt_f32_f16_e32 v154, v246
	v_rcp_f32_e32 v144, v144
	s_waitcnt lgkmcnt(0)
	v_fmac_f32_e32 v207, 0x3f1b4598, v199
	v_cndmask_b32_e64 v207, v207, v208, s[28:29]
	ds_bpermute_b32 v208, v125, v209
	ds_bpermute_b32 v125, v125, v210
	v_rcp_f32_e32 v145, v145
	v_cvt_f32_f16_e32 v179, v243
	v_pk_add_f32 v[154:155], v[154:155], v[148:149] neg_lo:[0,1] neg_hi:[0,1]
	s_waitcnt lgkmcnt(1)
	v_fmac_f32_e32 v208, 0x3f1b4598, v200
	v_cndmask_b32_e64 v208, v208, v209, s[28:29]
	v_add_u32_e32 v209, -16, v236
	v_cmp_lt_i32_e32 vcc, v209, v124
	s_waitcnt lgkmcnt(0)
	v_fmac_f32_e32 v125, 0x3f1b4598, v201
	v_cndmask_b32_e64 v125, v125, v210, s[28:29]
	v_cndmask_b32_e32 v209, v209, v236, vcc
	v_lshlrev_b32_e32 v209, 2, v209
	ds_bpermute_b32 v210, v209, v202
	v_pk_fma_f32 v[152:153], v[152:153], v[12:13], v[126:127]
	v_pk_add_f32 v[126:127], v[144:145], -1.0 op_sel_hi:[1,0]
	v_cvt_f32_f16_sdwa v147, v241 dst_sel:DWORD dst_unused:UNUSED_PAD src0_sel:WORD_1
	v_cvt_f32_f16_e32 v146, v241
	s_waitcnt lgkmcnt(0)
	v_add_f32_e32 v210, v202, v210
	v_cndmask_b32_e64 v202, v210, v202, s[30:31]
	ds_bpermute_b32 v210, v209, v203
	v_cvt_f32_f16_sdwa v161, v247 dst_sel:DWORD dst_unused:UNUSED_PAD src0_sel:WORD_1
	v_cvt_f32_f16_e32 v160, v247
	v_add_f32_e32 v150, v46, v179
	v_pk_fma_f32 v[148:149], v[154:155], v[16:17], v[148:149]
	s_waitcnt lgkmcnt(0)
	v_add_f32_e32 v210, v203, v210
	v_cndmask_b32_e64 v203, v210, v203, s[30:31]
	ds_bpermute_b32 v210, v209, v204
	v_pk_fma_f32 v[126:127], v[68:69], v[126:127], 1.0 op_sel_hi:[1,1,0]
	v_mul_f32_e32 v150, 0xbfb8aa3b, v150
	v_mul_f32_e32 v151, 0xbfb8aa3b, v151
	v_exp_f32_e32 v150, v150
	s_waitcnt lgkmcnt(0)
	v_add_f32_e32 v210, v204, v210
	v_cndmask_b32_e64 v204, v210, v204, s[30:31]
	ds_bpermute_b32 v210, v209, v205
	v_exp_f32_e32 v151, v151
	v_pk_add_f32 v[160:161], v[160:161], v[146:147] neg_lo:[0,1] neg_hi:[0,1]
	v_mul_f32_e32 v158, 0xbfb8aa3b, v158
	v_mul_f32_e32 v159, 0xbfb8aa3b, v159
	s_waitcnt lgkmcnt(0)
	v_add_f32_e32 v210, v205, v210
	v_cndmask_b32_e64 v205, v210, v205, s[30:31]
	ds_bpermute_b32 v210, v209, v206
	v_exp_f32_e32 v158, v158
	v_exp_f32_e32 v159, v159
	v_pk_mul_f32 v[154:155], v[148:149], v[60:61]
	v_pk_fma_f32 v[146:147], v[160:161], v[18:19], v[146:147]
	s_waitcnt lgkmcnt(0)
	v_add_f32_e32 v210, v206, v210
	v_cndmask_b32_e64 v206, v210, v206, s[30:31]
	ds_bpermute_b32 v210, v209, v207
	v_cvt_f32_f16_sdwa v129, v238 dst_sel:DWORD dst_unused:UNUSED_PAD src0_sel:WORD_1
	v_cvt_f32_f16_e32 v128, v238
	v_cvt_f32_f16_sdwa v157, v244 dst_sel:DWORD dst_unused:UNUSED_PAD src0_sel:WORD_1
	v_cvt_f32_f16_e32 v156, v244
	s_waitcnt lgkmcnt(0)
	v_add_f32_e32 v210, v207, v210
	v_cndmask_b32_e64 v207, v210, v207, s[30:31]
	ds_bpermute_b32 v210, v209, v208
	ds_bpermute_b32 v209, v209, v125
	v_add_f32_e32 v150, 1.0, v150
	v_add_f32_e32 v151, 1.0, v151
	v_pk_mul_f32 v[160:161], v[146:147], v[62:63]
	s_waitcnt lgkmcnt(1)
	v_add_f32_e32 v210, v208, v210
	s_waitcnt lgkmcnt(0)
	v_add_f32_e32 v209, v125, v209
	v_cndmask_b32_e64 v125, v209, v125, s[30:31]
	v_subrev_u32_e32 v209, 32, v236
	v_cmp_lt_i32_e32 vcc, v209, v124
	v_cndmask_b32_e64 v208, v210, v208, s[30:31]
	v_rcp_f32_e32 v150, v150
	v_cndmask_b32_e32 v124, v209, v236, vcc
	v_lshlrev_b32_e32 v124, 2, v124
	ds_bpermute_b32 v209, v124, v202
	v_rcp_f32_e32 v151, v151
	v_pk_mul_f32 v[170:171], v[168:169], v[56:57]
	v_add_f32_e32 v158, 1.0, v158
	v_add_f32_e32 v159, 1.0, v159
	s_waitcnt lgkmcnt(0)
	v_add_f32_e32 v209, v202, v209
	v_cndmask_b32_e64 v209, v209, v202, s[34:35]
	ds_bpermute_b32 v202, v124, v203
	v_fma_f32 v1, v1, s55, -v209
	v_mul_f32_e32 v1, 0x3fb8aa3b, v1
	v_pk_mul_f32 v[172:173], v[170:171], v[170:171]
	v_pk_add_f32 v[156:157], v[156:157], v[128:129] neg_lo:[0,1] neg_hi:[0,1]
	s_waitcnt lgkmcnt(0)
	v_add_f32_e32 v202, v203, v202
	v_cndmask_b32_e64 v210, v202, v203, s[34:35]
	ds_bpermute_b32 v202, v124, v204
	v_rcp_f32_e32 v158, v158
	v_rcp_f32_e32 v159, v159
	v_mul_f32_e32 v166, 0xbfb8aa3b, v166
	v_mul_f32_e32 v167, 0xbfb8aa3b, v167
	s_waitcnt lgkmcnt(0)
	v_add_f32_e32 v202, v204, v202
	v_cndmask_b32_e64 v211, v202, v204, s[34:35]
	ds_bpermute_b32 v202, v124, v205
	v_exp_f32_e32 v204, v1
	v_mul_f32_e32 v1, 0xbfb8aa3b, v210
	v_pk_mul_f32 v[176:177], v[174:175], v[58:59]
	v_exp_f32_e32 v166, v166
	s_waitcnt lgkmcnt(0)
	v_add_f32_e32 v202, v205, v202
	v_cndmask_b32_e64 v212, v202, v205, s[34:35]
	ds_bpermute_b32 v202, v124, v206
	v_exp_f32_e32 v167, v167
	v_pk_mul_f32 v[178:179], v[176:177], v[176:177]
	v_pk_fma_f32 v[156:157], v[156:157], v[14:15], v[128:129]
	v_pk_add_f32 v[128:129], v[150:151], -1.0 op_sel_hi:[1,0]
	s_waitcnt lgkmcnt(0)
	v_add_f32_e32 v202, v206, v202
	v_cndmask_b32_e64 v214, v202, v206, s[34:35]
	ds_bpermute_b32 v202, v124, v207
	v_pk_fma_f32 v[128:129], v[70:71], v[128:129], 1.0 op_sel_hi:[1,1,0]
	v_pk_fma_f32 v[162:163], v[162:163], v[8:9], v[130:131]
	v_pk_add_f32 v[130:131], v[158:159], -1.0 op_sel_hi:[1,0]
	v_cvt_f32_f16_sdwa v143, v239 dst_sel:DWORD dst_unused:UNUSED_PAD src0_sel:WORD_1
	s_waitcnt lgkmcnt(0)
; #define LAS __attribute__((address_space(3)))
; __device__ __forceinline__ float sum8(float x) { x += dppf<0xB1>(x); x += dppf<0x4E>(x); x += dppf<0x141>(x); return x; }
; __device__ __forceinline__ void st8(f16* p, const float (&v)[8]) { u32x4 w; w.x = pkh(v[0], v[1]); w.y = pkh(v[2], v[3]); w.z = pkh(v[4], v[5]); w.w = pkh(v[6], v[7]); *(u32x4*)p = w; }
; __global__ void __launch_bounds__(512, 2) fwd_megakernel(Params P) {
;     ...
;                                 ss = sum8(ss); bsum = sum8(bsum);
;                                 const float inv = __builtin_amdgcn_rsqf(fmaxf(ss, 1e-24f));
; #pragma unroll
;                                 for (int i = 0; i < 8; ++i) { const float kk = nk[i] * inv; nk[i] = -kk; bo[i] = kk * bo[i]; }
;                                 float G[8];
; #pragma unroll
;                                 for (int i = 0; i < 8; ++i) G[i] = ewv[i];
; #pragma unroll
;                                 for (int d = 8; d < 64; d <<= 1) {
; #pragma unroll
;                                     for (int i = 0; i < 8; ++i) { const float up = __shfl_up(G[i], d); if (lane >= d) G[i] += up; } }
;                                 float ecur[8];
; #pragma unroll
;                                 for (int i = 0; i < 8; ++i) { const float ec = __expf(-G[i]), ei = __expf(G[i]), ep = __expf(ewv[i] - G[i]);
;                                     ecur[i] = ec; nk[i] *= ep; ro[i] *= ec; bo[i] *= ei; ko[i] *= ei; }
;                                 LAS unsigned char* nbuf = lds + (c & 1) * 41984;
;                                 LAS unsigned char* nb = nbuf + loff;
;     ...
;                                 FS_PUT(0, nk); FS_PUT(1, bo); FS_PUT(2, ko); FS_PUT(3, ro); FS_PUT(4, vv);
;                                 if ((lane >> 3) == 7) { LAS unsigned char* gt = nbuf + 40960 + (tl >> 3) * 256 + seg * 32;
;                                     *(LAS f32x4*)(gt) = (f32x4){ecur[0], ecur[1], ecur[2], ecur[3]}; *(LAS f32x4*)(gt + 16) = (f32x4){ecur[4], ecur[5], ecur[6], ecur[7]}; }
;                                 if (half == 0) { const size_t o = gbase + (size_t)c * 32 * 1024;
;                                     st8(SI + ARR + o, vv);
;                                     if (L == 0) st8(VF + o, vv);
;                                     if (seg == 0) BS[(m0 + (size_t)c * 32 + tl) * 16 + h] = bsum; }
	v_add_f32_e32 v202, v207, v202
	v_cndmask_b32_e64 v215, v202, v207, s[34:35]
	ds_bpermute_b32 v202, v124, v208
	ds_bpermute_b32 v124, v124, v125
	v_pk_mul_f32 v[206:207], v[154:155], v[154:155]
	v_cvt_f32_f16_e32 v142, v239
	v_cvt_f32_f16_sdwa v165, v245 dst_sel:DWORD dst_unused:UNUSED_PAD src0_sel:WORD_1
	s_waitcnt lgkmcnt(1)
	v_add_f32_e32 v202, v208, v202
	s_waitcnt lgkmcnt(0)
	v_add_f32_e32 v124, v125, v124
	v_cndmask_b32_e64 v217, v124, v125, s[34:35]
	v_mul_f32_e32 v125, 0x3fb8aa3b, v209
	v_cndmask_b32_e64 v216, v202, v208, s[34:35]
	v_exp_f32_e32 v202, v125
	v_exp_f32_e32 v125, v1
	v_mul_f32_e32 v1, 0x3fb8aa3b, v210
	v_mul_f32_e32 v124, 0xbfb8aa3b, v209
	v_exp_f32_e32 v203, v1
	v_fma_f32 v1, v195, s55, -v210
	v_pk_mul_f32 v[208:209], v[148:149], v[126:127]
	v_mul_f32_e32 v1, 0x3fb8aa3b, v1
	v_pk_mul_f32 v[126:127], v[152:153], v[208:209]
	v_exp_f32_e32 v205, v1
	v_fma_f32 v1, v76, v126, 0
	v_fmac_f32_e32 v1, v77, v127
	v_mul_f32_e32 v127, 0x3fb8aa3b, v211
	v_exp_f32_e32 v210, v127
	v_fma_f32 v127, v196, s55, -v211
	v_mul_f32_e32 v127, 0x3fb8aa3b, v127
	v_mul_f32_e32 v149, 0x3fb8aa3b, v212
	v_mul_f32_e32 v126, 0xbfb8aa3b, v211
	v_exp_f32_e32 v148, v127
	v_mul_f32_e32 v127, 0xbfb8aa3b, v212
	v_exp_f32_e32 v211, v149
	v_fma_f32 v149, v198, s55, -v212
	v_pk_mul_f32 v[212:213], v[160:161], v[160:161]
	v_add_f32_e32 v195, v206, v207
	v_add_f32_e32 v195, v195, v212
	v_add_f32_e32 v195, v195, v213
	v_add_f32_e32 v172, v195, v172
	v_add_f32_e32 v172, v172, v173
	v_add_f32_e32 v172, v172, v178
	v_add_f32_e32 v172, v172, v179
	v_pk_mul_f32 v[178:179], v[146:147], v[128:129]
	v_cvt_f32_f16_e32 v164, v245
	v_pk_mul_f32 v[128:129], v[156:157], v[178:179]
	v_add_f32_e32 v166, 1.0, v166
	v_add_f32_e32 v167, 1.0, v167
	v_fmac_f32_e32 v1, v78, v128
	v_pk_fma_f32 v[130:131], v[64:65], v[130:131], 1.0 op_sel_hi:[1,1,0]
	v_rcp_f32_e32 v166, v166
	v_rcp_f32_e32 v167, v167
	v_add_f32_dpp v172, v172, v172 quad_perm:[1,0,3,2] row_mask:0xf bank_mask:0xf bound_ctrl:1
	v_fmac_f32_e32 v1, v79, v129
	v_mul_f32_e32 v129, 0x3fb8aa3b, v214
	v_mul_f32_e32 v146, 0x3fb8aa3b, v215
	v_pk_mul_f32 v[168:169], v[168:169], v[130:131]
	v_add_f32_dpp v172, v172, v172 quad_perm:[2,3,0,1] row_mask:0xf bank_mask:0xf bound_ctrl:1
	v_exp_f32_e32 v196, v129
	v_fma_f32 v129, v197, s55, -v214
	v_exp_f32_e32 v197, v146
	v_fma_f32 v146, v199, s55, -v215
	v_pk_mul_f32 v[130:131], v[162:163], v[168:169]
	v_add_f32_dpp v172, v172, v172 row_half_mirror row_mask:0xf bank_mask:0xf bound_ctrl:1
	v_mul_f32_e32 v146, 0x3fb8aa3b, v146
	v_fmac_f32_e32 v1, v72, v130
	v_pk_add_f32 v[164:165], v[164:165], v[142:143] neg_lo:[0,1] neg_hi:[0,1]
	v_max_f32_e32 v172, 0x179abe15, v172
	v_exp_f32_e32 v199, v146
	v_fmac_f32_e32 v1, v73, v131
	v_mul_f32_e32 v131, 0x3fb8aa3b, v216
	v_mul_f32_e32 v146, 0x3fb8aa3b, v217
	v_mul_f32_e32 v149, 0x3fb8aa3b, v149
	v_rsq_f32_e32 v172, v172
	v_exp_f32_e32 v206, v131
	v_fma_f32 v131, v200, s55, -v216
	v_exp_f32_e32 v207, v146
	v_fma_f32 v146, v201, s55, -v217
	v_pk_fma_f32 v[164:165], v[164:165], v[10:11], v[142:143]
	v_pk_add_f32 v[142:143], v[166:167], -1.0 op_sel_hi:[1,0]
	v_exp_f32_e32 v149, v149
	v_mul_f32_e32 v129, 0x3fb8aa3b, v129
	v_mul_f32_e32 v131, 0x3fb8aa3b, v131
	v_mul_f32_e32 v146, 0x3fb8aa3b, v146
	v_pk_fma_f32 v[142:143], v[66:67], v[142:143], 1.0 op_sel_hi:[1,1,0]
	v_exp_f32_e32 v198, v129
	v_exp_f32_e32 v200, v131
	v_exp_f32_e32 v201, v146
	v_pk_mul_f32 v[174:175], v[174:175], v[142:143]
	s_bitcmp1_b32 s40, 0
	v_pk_mul_f32 v[142:143], v[164:165], v[174:175]
	s_cselect_b32 s39, 0xa400, 0
	v_pk_mul_f32 v[154:155], v[172:173], v[154:155] op_sel_hi:[0,1]
	v_pk_mul_f32 v[160:161], v[172:173], v[160:161] op_sel_hi:[0,1]
	v_fmac_f32_e32 v1, v74, v142
	s_add_i32 s39, s39, 0
	v_pk_mul_f32 v[170:171], v[172:173], v[170:171] op_sel_hi:[0,1]
	v_pk_mul_f32 v[172:173], v[172:173], v[176:177] op_sel_hi:[0,1]
	v_fmac_f32_e32 v1, v75, v143
	v_add3_u32 v143, s39, v183, v181
	v_pk_mul_f32 v[148:149], v[148:149], v[160:161] neg_lo:[0,1] neg_hi:[0,1]
	v_pk_mul_f32 v[146:147], v[204:205], v[154:155] neg_lo:[0,1] neg_hi:[0,1]
	ds_write_b128 v143, v[146:149]
	v_pk_mul_f32 v[148:149], v[200:201], v[172:173] neg_lo:[0,1] neg_hi:[0,1]
	v_pk_mul_f32 v[146:147], v[198:199], v[170:171] neg_lo:[0,1] neg_hi:[0,1]
	ds_write_b128 v143, v[146:149] offset:16
	v_pk_mul_f32 v[144:145], v[154:155], v[144:145]
	v_pk_mul_f32 v[146:147], v[160:161], v[150:151]
	v_pk_mul_f32 v[144:145], v[202:203], v[144:145]
	v_pk_mul_f32 v[146:147], v[210:211], v[146:147]
	v_exp_f32_e32 v124, v124
	v_exp_f32_e32 v126, v126
	v_exp_f32_e32 v127, v127
	v_mul_f32_e32 v128, 0xbfb8aa3b, v214
	v_mul_f32_e32 v129, 0xbfb8aa3b, v215
	v_mul_f32_e32 v130, 0xbfb8aa3b, v216
	v_mul_f32_e32 v131, 0xbfb8aa3b, v217
	ds_write_b128 v143, v[144:147] offset:256
	v_pk_mul_f32 v[144:145], v[170:171], v[158:159]
	v_pk_mul_f32 v[146:147], v[172:173], v[166:167]
	v_exp_f32_e32 v128, v128
	v_exp_f32_e32 v129, v129
	v_exp_f32_e32 v130, v130
	v_exp_f32_e32 v131, v131
	v_pk_mul_f32 v[144:145], v[196:197], v[144:145]
	v_pk_mul_f32 v[146:147], v[206:207], v[146:147]
	ds_write_b128 v143, v[144:147] offset:272
	v_pk_mul_f32 v[144:145], v[202:203], v[208:209]
	v_pk_mul_f32 v[146:147], v[210:211], v[178:179]
	v_add_f32_dpp v1, v1, v1 quad_perm:[1,0,3,2] row_mask:0xf bank_mask:0xf bound_ctrl:1
	ds_write_b128 v143, v[144:147] offset:512
	v_pk_mul_f32 v[144:145], v[196:197], v[168:169]
	v_pk_mul_f32 v[146:147], v[206:207], v[174:175]
	v_add_f32_dpp v1, v1, v1 quad_perm:[2,3,0,1] row_mask:0xf bank_mask:0xf bound_ctrl:1
	ds_write_b128 v143, v[144:147] offset:528
	v_pk_mul_f32 v[144:145], v[124:125], v[152:153]
	v_pk_mul_f32 v[146:147], v[126:127], v[156:157]
	v_mov_b32_dpp v142, v1 row_half_mirror row_mask:0xf bank_mask:0xf bound_ctrl:1
	ds_write_b128 v143, v[144:147] offset:768
	v_pk_mul_f32 v[144:145], v[128:129], v[162:163]
	v_pk_mul_f32 v[146:147], v[130:131], v[164:165]
	ds_write_b128 v143, v[144:147] offset:784
	ds_write_b128 v143, v[116:119] offset:1024
	ds_write_b128 v143, v[120:123] offset:1040
	s_and_saveexec_b64 s[62:63], s[10:11]
	s_cbranch_execz .LBB0_273
	v_add3_u32 v143, s39, v194, v181
	ds_write_b128 v143, v[124:127] offset:40960
	ds_write_b128 v143, v[128:131] offset:40976
	s_or_b64 exec, exec, s[62:63]
	s_andn2_b64 vcc, exec, s[94:95]
	v_lshl_add_u64 v[124:125], v[2:3], 0, s[92:93]
	s_cbranch_vccz .LBB0_274

; __device__ __forceinline__ void st8(f16* p, const float (&v)[8]) { u32x4 w; w.x = pkh(v[0], v[1]); w.y = pkh(v[2], v[3]); w.z = pkh(v[4], v[5]); w.w = pkh(v[6], v[7]); *(u32x4*)p = w; }
; __global__ void __launch_bounds__(512, 2) fwd_megakernel(Params P) {
;     ...
;                                 if (half == 0) { const size_t o = gbase + (size_t)c * 32 * 1024;
;                                     st8(SI + ARR + o, vv);
;                                     if (L == 0) st8(VF + o, vv);
;                                     if (seg == 0) BS[(m0 + (size_t)c * 32 + tl) * 16 + h] = bsum; }
;                                 if (c + 1 < NC) FS_LOAD(c + 1);
.LBB0_277:
	s_or_b64 exec, exec, s[62:63]
	s_cmpk_gt_u32 s40, 0x7e
	s_cbranch_scc1 .LBB0_264
.LBB0_278:
	s_branch .LBB0_264
.LBB0_282:
	v_add_co_u32_e32 v120, vcc, 0x3c000000, v124
	s_nop 1
	v_addc_co_u32_e32 v121, vcc, 0, v125, vcc
	global_store_dwordx4 v[120:121], v[116:119], off
	s_and_saveexec_b64 s[62:63], s[12:13]
	s_cbranch_execnz .LBB0_276
	s_branch .LBB0_277

; __global__ void __launch_bounds__(512, 2) fwd_megakernel(Params P) {
;     extern __shared__ __attribute__((aligned(16))) unsigned char smem[];
	.amdhsa_kernel _Z14fwd_megakernel6Params
		.amdhsa_group_segment_fixed_size 0
		.amdhsa_private_segment_fixed_size 0
		.amdhsa_kernarg_size 464
		.amdhsa_user_sgpr_count 2
		.amdhsa_user_sgpr_dispatch_ptr 0
		.amdhsa_user_sgpr_queue_ptr 0
		.amdhsa_user_sgpr_kernarg_segment_ptr 1
		.amdhsa_user_sgpr_dispatch_id 0
		.amdhsa_user_sgpr_kernarg_preload_length 0
		.amdhsa_user_sgpr_kernarg_preload_offset 0
		.amdhsa_user_sgpr_private_segment_size 0
		.amdhsa_uses_dynamic_stack 0
		.amdhsa_enable_private_segment 0
		.amdhsa_system_sgpr_workgroup_id_x 1
		.amdhsa_system_sgpr_workgroup_id_y 0
		.amdhsa_system_sgpr_workgroup_id_z 0
		.amdhsa_system_sgpr_workgroup_info 0
		.amdhsa_system_vgpr_workitem_id 2
		.amdhsa_next_free_vgpr 256
		.amdhsa_next_free_sgpr 102
		.amdhsa_accum_offset 256
		.amdhsa_reserve_vcc 1
		.amdhsa_float_round_mode_32 0
		.amdhsa_float_round_mode_16_64 0
		.amdhsa_float_denorm_mode_32 3
		.amdhsa_float_denorm_mode_16_64 3
		.amdhsa_dx10_clamp 1
		.amdhsa_ieee_mode 1
		.amdhsa_fp16_overflow 0
		.amdhsa_tg_split 0
		.amdhsa_exception_fp_ieee_invalid_op 0
		.amdhsa_exception_fp_denorm_src 0
		.amdhsa_exception_fp_ieee_div_zero 0
		.amdhsa_exception_fp_ieee_overflow 0
		.amdhsa_exception_fp_ieee_underflow 0
		.amdhsa_exception_fp_ieee_inexact 0
		.amdhsa_exception_int_div_zero 0
	.end_amdhsa_kernel

; __global__ void __launch_bounds__(512, 2) fwd_megakernel(Params P) {
;     extern __shared__ __attribute__((aligned(16))) unsigned char smem[];
amdhsa.kernels:
  - .agpr_count:     0
    .args:
      - .offset:         0
        .size:           208
        .value_kind:     by_value
      - .offset:         208
        .size:           4
        .value_kind:     hidden_block_count_x
      - .offset:         212
        .size:           4
        .value_kind:     hidden_block_count_y
      - .offset:         216
        .size:           4
        .value_kind:     hidden_block_count_z
      - .offset:         220
        .size:           2
        .value_kind:     hidden_group_size_x
      - .offset:         222
        .size:           2
        .value_kind:     hidden_group_size_y
      - .offset:         224
        .size:           2
        .value_kind:     hidden_group_size_z
      - .offset:         226
        .size:           2
        .value_kind:     hidden_remainder_x
      - .offset:         228
        .size:           2
        .value_kind:     hidden_remainder_y
      - .offset:         230
        .size:           2
        .value_kind:     hidden_remainder_z
      - .offset:         248
        .size:           8
        .value_kind:     hidden_global_offset_x
      - .offset:         256
        .size:           8
        .value_kind:     hidden_global_offset_y
      - .offset:         264
        .size:           8
        .value_kind:     hidden_global_offset_z
      - .offset:         272
        .size:           2
        .value_kind:     hidden_grid_dims
      - .offset:         296
        .size:           8
        .value_kind:     hidden_multigrid_sync_arg
      - .offset:         328
        .size:           4
        .value_kind:     hidden_dynamic_lds_size
    .group_segment_fixed_size: 0
    .kernarg_segment_align: 8
    .kernarg_segment_size: 464
    .language:       OpenCL C
    .language_version:
      - 2
      - 0
    .max_flat_workgroup_size: 512
    .name:           _Z14fwd_megakernel6Params
    .private_segment_fixed_size: 0
    .sgpr_count:     108
    .sgpr_spill_count: 82
    .symbol:         _Z14fwd_megakernel6Params.kd
    .uniform_work_group_size: 1
    .uses_dynamic_stack: false
    .vgpr_count:     256
    .vgpr_spill_count: 0
    .wavefront_size: 64
